# GEMM1 epilogue: lane-index rotation via ds_bpermute so each lane quad stores 64 contiguous bytes of p, exchange latency pipelined one group behind
# speedup vs baseline: 1.0232x; 1.0066x over previous
.LBB0_120:
	s_lshl_b32 s27, s54, 8
	s_or_b32 s54, s27, s70
	v_readfirstlane_b32 s30, v143
	v_and_b32_e32 v212, 3, v180
	v_lshrrev_b32_e32 v213, 2, v180
	s_lshl_b32 s31, s38, 8
	v_lshl_or_b32 v212, v212, 4, v213
	s_add_i32 s30, s30, s31
	v_mul_u32_u24_e32 v213, 0x2100, v213
	s_mul_i32 s30, s30, 0x2100
	v_and_b32_e32 v214, 3, v180
	s_lshl_b32 s31, s54, 1
	v_lshlrev_b32_e32 v212, 2, v212
	s_add_u32 s30, s30, s31
	v_lshl_add_u32 v213, v214, 4, v213
	s_add_u32 s30, s78, s30
	s_addc_u32 s31, s79, 0
	s_cmpk_gt_i32 s54, 0x107f
	v_lshl_add_u32 v181, s38, 8, v143
	s_cbranch_scc0 .LBB0_123
	s_or_b32 s28, s54, 0x80
	s_cmpk_gt_i32 s28, 0x107f
	s_cbranch_scc0 .LBB0_532

.LBB0_174:
	v_or_b32_e32 v160, s54, v150
	v_mov_b64_e32 v[124:125], s[78:79]
	v_ashrrev_i32_e32 v161, 31, v160
	v_mad_i64_i32 v[124:125], s[28:29], v181, s26, v[124:125]
	v_cvt_pk_bf16_f32 v120, v128, v129
	v_cvt_pk_bf16_f32 v121, v130, v131
	v_cvt_pk_bf16_f32 v122, v132, v133
	v_cvt_pk_bf16_f32 v123, v134, v135
	v_lshl_add_u64 v[124:125], v[160:161], 1, v[124:125]
	s_and_b64 vcc, exec, s[38:39]
	v_or_b32_e32 v128, 16, v181
	ds_bpermute_b32 v214, v212, v120
	ds_bpermute_b32 v215, v212, v121
	ds_bpermute_b32 v216, v212, v122
	ds_bpermute_b32 v217, v212, v123
	s_cbranch_vccnz .LBB0_224
	v_add_u32_e32 v182, 16, v181
	v_xor_b32_e32 v183, 16, v180
	v_and_b32_e32 v182, 0xfff, v182
	v_lshlrev_b32_e32 v183, 2, v183
	v_cvt_f32_u32_e32 v182, v182
	v_cmp_eq_u32_e64 s[60:61], 0, v171
	v_cmp_gt_u32_e64 s[68:69], 2, v171
	ds_bpermute_b32 v184, v183, v112
	ds_bpermute_b32 v185, v183, v113
	ds_bpermute_b32 v186, v183, v114
	ds_bpermute_b32 v187, v183, v115
	ds_bpermute_b32 v188, v183, v116
	ds_bpermute_b32 v189, v183, v117
	ds_bpermute_b32 v190, v183, v118
	ds_bpermute_b32 v191, v183, v119
	v_mov_b32_e32 v192, 1.0
	v_cndmask_b32_e64 v192, v192, -1.0, s[60:61]
	v_mul_f32_e32 v194, 0.15915494, v182
	v_rndne_f32_e32 v194, v194
	v_fma_f32 v194, v182, 0.15915494, -v194
	v_mul_f32_e32 v194, 0x40c90fdb, v194
	v_mul_f32_e32 v194, 0.15915494, v194
	v_sin_f32_e32 v204, v194
	v_cos_f32_e32 v196, v194
	v_mul_f32_e32 v193, 0x3e4693af, v182
	v_mul_f32_e32 v194, 0.15915494, v193
	v_rndne_f32_e32 v194, v194
	v_fma_f32 v194, v193, 0.15915494, -v194
	v_mul_f32_e32 v194, 0x40c90fdb, v194
	v_mul_f32_e32 v194, 0.15915494, v194
	v_sin_f32_e32 v205, v194
	v_cos_f32_e32 v197, v194
	v_mul_f32_e32 v193, 0x3d1a08c8, v182
	v_mul_f32_e32 v194, 0.15915494, v193
	v_rndne_f32_e32 v194, v194
	v_fma_f32 v194, v193, 0.15915494, -v194
	v_mul_f32_e32 v194, 0x40c90fdb, v194
	v_mul_f32_e32 v194, 0.15915494, v194
	v_sin_f32_e32 v206, v194
	v_cos_f32_e32 v198, v194
	v_mul_f32_e32 v193, 0x3beef74e, v182
	v_mul_f32_e32 v194, 0.15915494, v193
	v_rndne_f32_e32 v194, v194
	v_fma_f32 v194, v193, 0.15915494, -v194
	v_mul_f32_e32 v194, 0x40c90fdb, v194
	v_mul_f32_e32 v194, 0.15915494, v194
	v_sin_f32_e32 v207, v194
	v_cos_f32_e32 v199, v194
	v_mul_f32_e32 v193, 0x3ab95d22, v182
	v_mul_f32_e32 v194, 0.15915494, v193
	v_rndne_f32_e32 v194, v194
	v_fma_f32 v194, v193, 0.15915494, -v194
	v_mul_f32_e32 v194, 0x40c90fdb, v194
	v_mul_f32_e32 v194, 0.15915494, v194
	v_sin_f32_e32 v208, v194
	v_cos_f32_e32 v200, v194
	v_mul_f32_e32 v193, 0x398fc8f8, v182
	v_mul_f32_e32 v194, 0.15915494, v193
	v_rndne_f32_e32 v194, v194
	v_fma_f32 v194, v193, 0.15915494, -v194
	v_mul_f32_e32 v194, 0x40c90fdb, v194
	v_mul_f32_e32 v194, 0.15915494, v194
	v_sin_f32_e32 v209, v194
	v_cos_f32_e32 v201, v194
	v_mul_f32_e32 v193, 0x385f10c4, v182
	v_mul_f32_e32 v194, 0.15915494, v193
	v_rndne_f32_e32 v194, v194
	v_fma_f32 v194, v193, 0.15915494, -v194
	v_mul_f32_e32 v194, 0x40c90fdb, v194
	v_mul_f32_e32 v194, 0.15915494, v194
	v_sin_f32_e32 v210, v194
	v_cos_f32_e32 v202, v194
	v_mul_f32_e32 v193, 0x372d07a7, v182
	v_mul_f32_e32 v194, 0.15915494, v193
	v_rndne_f32_e32 v194, v194
	v_fma_f32 v194, v193, 0.15915494, -v194
	v_mul_f32_e32 v194, 0x40c90fdb, v194
	v_mul_f32_e32 v194, 0.15915494, v194
	v_sin_f32_e32 v211, v194
	v_cos_f32_e32 v203, v194
	s_waitcnt lgkmcnt(0)
	v_mul_f32_e32 v204, v204, v184
	v_mul_f32_e32 v196, v196, v112
	v_mul_f32_e32 v204, v204, v192
	v_add_f32_e32 v196, v196, v204
	v_cndmask_b32_e64 v120, v112, v196, s[68:69]
	v_mul_f32_e32 v205, v205, v185
	v_mul_f32_e32 v197, v197, v113
	v_mul_f32_e32 v205, v205, v192
	v_add_f32_e32 v197, v197, v205
	v_cndmask_b32_e64 v121, v113, v197, s[68:69]
	v_mul_f32_e32 v206, v206, v186
	v_mul_f32_e32 v198, v198, v114
	v_mul_f32_e32 v206, v206, v192
	v_add_f32_e32 v198, v198, v206
	v_cndmask_b32_e64 v122, v114, v198, s[68:69]
	v_mul_f32_e32 v207, v207, v187
	v_mul_f32_e32 v199, v199, v115
	v_mul_f32_e32 v207, v207, v192
	v_add_f32_e32 v199, v199, v207
	v_cndmask_b32_e64 v123, v115, v199, s[68:69]
	v_mul_f32_e32 v208, v208, v188
	v_mul_f32_e32 v200, v200, v116
	v_mul_f32_e32 v208, v208, v192
	v_add_f32_e32 v200, v200, v208
	v_cndmask_b32_e64 v124, v116, v200, s[68:69]
	v_mul_f32_e32 v209, v209, v189
	v_mul_f32_e32 v201, v201, v117
	v_mul_f32_e32 v209, v209, v192
	v_add_f32_e32 v201, v201, v209
	v_cndmask_b32_e64 v125, v117, v201, s[68:69]
	v_mul_f32_e32 v210, v210, v190
	v_mul_f32_e32 v202, v202, v118
	v_mul_f32_e32 v210, v210, v192
	v_add_f32_e32 v202, v202, v210
	v_cndmask_b32_e64 v126, v118, v202, s[68:69]
	v_mul_f32_e32 v211, v211, v191
	v_mul_f32_e32 v203, v203, v119
	v_mul_f32_e32 v211, v211, v192
	v_add_f32_e32 v203, v203, v211
	v_cndmask_b32_e64 v127, v119, v203, s[68:69]
	s_branch .LBB0_225

.LBB0_225:
	v_mov_b64_e32 v[116:117], s[78:79]
	v_mad_i64_i32 v[116:117], s[28:29], v128, s26, v[116:117]
	v_cvt_pk_bf16_f32 v112, v120, v121
	v_cvt_pk_bf16_f32 v113, v122, v123
	v_cvt_pk_bf16_f32 v114, v124, v125
	v_cvt_pk_bf16_f32 v115, v126, v127
	v_lshl_add_u64 v[116:117], v[160:161], 1, v[116:117]
	s_and_b64 vcc, exec, s[38:39]
	v_or_b32_e32 v120, 32, v181
	s_waitcnt lgkmcnt(0)
	s_mov_b64 s[68:69], s[30:31]
	global_store_dwordx4 v213, v[214:217], s[68:69] nt
	ds_bpermute_b32 v218, v212, v112
	ds_bpermute_b32 v219, v212, v113
	ds_bpermute_b32 v220, v212, v114
	ds_bpermute_b32 v221, v212, v115
	s_cbranch_vccnz .LBB0_275
	v_add_u32_e32 v182, 32, v181
	v_xor_b32_e32 v183, 16, v180
	v_and_b32_e32 v182, 0xfff, v182
	v_lshlrev_b32_e32 v183, 2, v183
	v_cvt_f32_u32_e32 v182, v182
	v_cmp_eq_u32_e64 s[60:61], 0, v171
	v_cmp_gt_u32_e64 s[68:69], 2, v171
	ds_bpermute_b32 v184, v183, v104
	ds_bpermute_b32 v185, v183, v105
	ds_bpermute_b32 v186, v183, v106
	ds_bpermute_b32 v187, v183, v107
	ds_bpermute_b32 v188, v183, v108
	ds_bpermute_b32 v189, v183, v109
	ds_bpermute_b32 v190, v183, v110
	ds_bpermute_b32 v191, v183, v111
	v_mov_b32_e32 v192, 1.0
	v_cndmask_b32_e64 v192, v192, -1.0, s[60:61]
	v_mul_f32_e32 v194, 0.15915494, v182
	v_rndne_f32_e32 v194, v194
	v_fma_f32 v194, v182, 0.15915494, -v194
	v_mul_f32_e32 v194, 0x40c90fdb, v194
	v_mul_f32_e32 v194, 0.15915494, v194
	v_sin_f32_e32 v204, v194
	v_cos_f32_e32 v196, v194
	v_mul_f32_e32 v193, 0x3e4693af, v182
	v_mul_f32_e32 v194, 0.15915494, v193
	v_rndne_f32_e32 v194, v194
	v_fma_f32 v194, v193, 0.15915494, -v194
	v_mul_f32_e32 v194, 0x40c90fdb, v194
	v_mul_f32_e32 v194, 0.15915494, v194
	v_sin_f32_e32 v205, v194
	v_cos_f32_e32 v197, v194
	v_mul_f32_e32 v193, 0x3d1a08c8, v182
	v_mul_f32_e32 v194, 0.15915494, v193
	v_rndne_f32_e32 v194, v194
	v_fma_f32 v194, v193, 0.15915494, -v194
	v_mul_f32_e32 v194, 0x40c90fdb, v194
	v_mul_f32_e32 v194, 0.15915494, v194
	v_sin_f32_e32 v206, v194
	v_cos_f32_e32 v198, v194
	v_mul_f32_e32 v193, 0x3beef74e, v182
	v_mul_f32_e32 v194, 0.15915494, v193
	v_rndne_f32_e32 v194, v194
	v_fma_f32 v194, v193, 0.15915494, -v194
	v_mul_f32_e32 v194, 0x40c90fdb, v194
	v_mul_f32_e32 v194, 0.15915494, v194
	v_sin_f32_e32 v207, v194
	v_cos_f32_e32 v199, v194
	v_mul_f32_e32 v193, 0x3ab95d22, v182
	v_mul_f32_e32 v194, 0.15915494, v193
	v_rndne_f32_e32 v194, v194
	v_fma_f32 v194, v193, 0.15915494, -v194
	v_mul_f32_e32 v194, 0x40c90fdb, v194
	v_mul_f32_e32 v194, 0.15915494, v194
	v_sin_f32_e32 v208, v194
	v_cos_f32_e32 v200, v194
	v_mul_f32_e32 v193, 0x398fc8f8, v182
	v_mul_f32_e32 v194, 0.15915494, v193
	v_rndne_f32_e32 v194, v194
	v_fma_f32 v194, v193, 0.15915494, -v194
	v_mul_f32_e32 v194, 0x40c90fdb, v194
	v_mul_f32_e32 v194, 0.15915494, v194
	v_sin_f32_e32 v209, v194
	v_cos_f32_e32 v201, v194
	v_mul_f32_e32 v193, 0x385f10c4, v182
	v_mul_f32_e32 v194, 0.15915494, v193
	v_rndne_f32_e32 v194, v194
	v_fma_f32 v194, v193, 0.15915494, -v194
	v_mul_f32_e32 v194, 0x40c90fdb, v194
	v_mul_f32_e32 v194, 0.15915494, v194
	v_sin_f32_e32 v210, v194
	v_cos_f32_e32 v202, v194
	v_mul_f32_e32 v193, 0x372d07a7, v182
	v_mul_f32_e32 v194, 0.15915494, v193
	v_rndne_f32_e32 v194, v194
	v_fma_f32 v194, v193, 0.15915494, -v194
	v_mul_f32_e32 v194, 0x40c90fdb, v194
	v_mul_f32_e32 v194, 0.15915494, v194
	v_sin_f32_e32 v211, v194
	v_cos_f32_e32 v203, v194
	s_waitcnt lgkmcnt(0)
	v_mul_f32_e32 v204, v204, v184
	v_mul_f32_e32 v196, v196, v104
	v_mul_f32_e32 v204, v204, v192
	v_add_f32_e32 v196, v196, v204
	v_cndmask_b32_e64 v112, v104, v196, s[68:69]
	v_mul_f32_e32 v205, v205, v185
	v_mul_f32_e32 v197, v197, v105
	v_mul_f32_e32 v205, v205, v192
	v_add_f32_e32 v197, v197, v205
	v_cndmask_b32_e64 v113, v105, v197, s[68:69]
	v_mul_f32_e32 v206, v206, v186
	v_mul_f32_e32 v198, v198, v106
	v_mul_f32_e32 v206, v206, v192
	v_add_f32_e32 v198, v198, v206
	v_cndmask_b32_e64 v114, v106, v198, s[68:69]
	v_mul_f32_e32 v207, v207, v187
	v_mul_f32_e32 v199, v199, v107
	v_mul_f32_e32 v207, v207, v192
	v_add_f32_e32 v199, v199, v207
	v_cndmask_b32_e64 v115, v107, v199, s[68:69]
	v_mul_f32_e32 v208, v208, v188
	v_mul_f32_e32 v200, v200, v108
	v_mul_f32_e32 v208, v208, v192
	v_add_f32_e32 v200, v200, v208
	v_cndmask_b32_e64 v116, v108, v200, s[68:69]
	v_mul_f32_e32 v209, v209, v189
	v_mul_f32_e32 v201, v201, v109
	v_mul_f32_e32 v209, v209, v192
	v_add_f32_e32 v201, v201, v209
	v_cndmask_b32_e64 v117, v109, v201, s[68:69]
	v_mul_f32_e32 v210, v210, v190
	v_mul_f32_e32 v202, v202, v110
	v_mul_f32_e32 v210, v210, v192
	v_add_f32_e32 v202, v202, v210
	v_cndmask_b32_e64 v118, v110, v202, s[68:69]
	v_mul_f32_e32 v211, v211, v191
	v_mul_f32_e32 v203, v203, v111
	v_mul_f32_e32 v211, v211, v192
	v_add_f32_e32 v203, v203, v211
	v_cndmask_b32_e64 v119, v111, v203, s[68:69]
	s_branch .LBB0_276

.LBB0_276:
	v_mov_b64_e32 v[108:109], s[78:79]
	v_mad_i64_i32 v[108:109], s[28:29], v120, s26, v[108:109]
	v_cvt_pk_bf16_f32 v104, v112, v113
	v_cvt_pk_bf16_f32 v105, v114, v115
	v_cvt_pk_bf16_f32 v106, v116, v117
	v_cvt_pk_bf16_f32 v107, v118, v119
	v_lshl_add_u64 v[108:109], v[160:161], 1, v[108:109]
	s_and_b64 vcc, exec, s[38:39]
	v_or_b32_e32 v112, 48, v181
	s_waitcnt lgkmcnt(0)
	s_add_u32 s68, s30, 0x21000
	s_addc_u32 s69, s31, 0
	global_store_dwordx4 v213, v[218:221], s[68:69] nt
	ds_bpermute_b32 v214, v212, v104
	ds_bpermute_b32 v215, v212, v105
	ds_bpermute_b32 v216, v212, v106
	ds_bpermute_b32 v217, v212, v107
	s_cbranch_vccnz .LBB0_326
	v_add_u32_e32 v182, 48, v181
	v_xor_b32_e32 v183, 16, v180
	v_and_b32_e32 v182, 0xfff, v182
	v_lshlrev_b32_e32 v183, 2, v183
	v_cvt_f32_u32_e32 v182, v182
	v_cmp_eq_u32_e64 s[60:61], 0, v171
	v_cmp_gt_u32_e64 s[68:69], 2, v171
	ds_bpermute_b32 v184, v183, v96
	ds_bpermute_b32 v185, v183, v97
	ds_bpermute_b32 v186, v183, v98
	ds_bpermute_b32 v187, v183, v99
	ds_bpermute_b32 v188, v183, v100
	ds_bpermute_b32 v189, v183, v101
	ds_bpermute_b32 v190, v183, v102
	ds_bpermute_b32 v191, v183, v103
	v_mov_b32_e32 v192, 1.0
	v_cndmask_b32_e64 v192, v192, -1.0, s[60:61]
	v_mul_f32_e32 v194, 0.15915494, v182
	v_rndne_f32_e32 v194, v194
	v_fma_f32 v194, v182, 0.15915494, -v194
	v_mul_f32_e32 v194, 0x40c90fdb, v194
	v_mul_f32_e32 v194, 0.15915494, v194
	v_sin_f32_e32 v204, v194
	v_cos_f32_e32 v196, v194
	v_mul_f32_e32 v193, 0x3e4693af, v182
	v_mul_f32_e32 v194, 0.15915494, v193
	v_rndne_f32_e32 v194, v194
	v_fma_f32 v194, v193, 0.15915494, -v194
	v_mul_f32_e32 v194, 0x40c90fdb, v194
	v_mul_f32_e32 v194, 0.15915494, v194
	v_sin_f32_e32 v205, v194
	v_cos_f32_e32 v197, v194
	v_mul_f32_e32 v193, 0x3d1a08c8, v182
	v_mul_f32_e32 v194, 0.15915494, v193
	v_rndne_f32_e32 v194, v194
	v_fma_f32 v194, v193, 0.15915494, -v194
	v_mul_f32_e32 v194, 0x40c90fdb, v194
	v_mul_f32_e32 v194, 0.15915494, v194
	v_sin_f32_e32 v206, v194
	v_cos_f32_e32 v198, v194
	v_mul_f32_e32 v193, 0x3beef74e, v182
	v_mul_f32_e32 v194, 0.15915494, v193
	v_rndne_f32_e32 v194, v194
	v_fma_f32 v194, v193, 0.15915494, -v194
	v_mul_f32_e32 v194, 0x40c90fdb, v194
	v_mul_f32_e32 v194, 0.15915494, v194
	v_sin_f32_e32 v207, v194
	v_cos_f32_e32 v199, v194
	v_mul_f32_e32 v193, 0x3ab95d22, v182
	v_mul_f32_e32 v194, 0.15915494, v193
	v_rndne_f32_e32 v194, v194
	v_fma_f32 v194, v193, 0.15915494, -v194
	v_mul_f32_e32 v194, 0x40c90fdb, v194
	v_mul_f32_e32 v194, 0.15915494, v194
	v_sin_f32_e32 v208, v194
	v_cos_f32_e32 v200, v194
	v_mul_f32_e32 v193, 0x398fc8f8, v182
	v_mul_f32_e32 v194, 0.15915494, v193
	v_rndne_f32_e32 v194, v194
	v_fma_f32 v194, v193, 0.15915494, -v194
	v_mul_f32_e32 v194, 0x40c90fdb, v194
	v_mul_f32_e32 v194, 0.15915494, v194
	v_sin_f32_e32 v209, v194
	v_cos_f32_e32 v201, v194
	v_mul_f32_e32 v193, 0x385f10c4, v182
	v_mul_f32_e32 v194, 0.15915494, v193
	v_rndne_f32_e32 v194, v194
	v_fma_f32 v194, v193, 0.15915494, -v194
	v_mul_f32_e32 v194, 0x40c90fdb, v194
	v_mul_f32_e32 v194, 0.15915494, v194
	v_sin_f32_e32 v210, v194
	v_cos_f32_e32 v202, v194
	v_mul_f32_e32 v193, 0x372d07a7, v182
	v_mul_f32_e32 v194, 0.15915494, v193
	v_rndne_f32_e32 v194, v194
	v_fma_f32 v194, v193, 0.15915494, -v194
	v_mul_f32_e32 v194, 0x40c90fdb, v194
	v_mul_f32_e32 v194, 0.15915494, v194
	v_sin_f32_e32 v211, v194
	v_cos_f32_e32 v203, v194
	s_waitcnt lgkmcnt(0)
	v_mul_f32_e32 v204, v204, v184
	v_mul_f32_e32 v196, v196, v96
	v_mul_f32_e32 v204, v204, v192
	v_add_f32_e32 v196, v196, v204
	v_cndmask_b32_e64 v104, v96, v196, s[68:69]
	v_mul_f32_e32 v205, v205, v185
	v_mul_f32_e32 v197, v197, v97
	v_mul_f32_e32 v205, v205, v192
	v_add_f32_e32 v197, v197, v205
	v_cndmask_b32_e64 v105, v97, v197, s[68:69]
	v_mul_f32_e32 v206, v206, v186
	v_mul_f32_e32 v198, v198, v98
	v_mul_f32_e32 v206, v206, v192
	v_add_f32_e32 v198, v198, v206
	v_cndmask_b32_e64 v106, v98, v198, s[68:69]
	v_mul_f32_e32 v207, v207, v187
	v_mul_f32_e32 v199, v199, v99
	v_mul_f32_e32 v207, v207, v192
	v_add_f32_e32 v199, v199, v207
	v_cndmask_b32_e64 v107, v99, v199, s[68:69]
	v_mul_f32_e32 v208, v208, v188
	v_mul_f32_e32 v200, v200, v100
	v_mul_f32_e32 v208, v208, v192
	v_add_f32_e32 v200, v200, v208
	v_cndmask_b32_e64 v108, v100, v200, s[68:69]
	v_mul_f32_e32 v209, v209, v189
	v_mul_f32_e32 v201, v201, v101
	v_mul_f32_e32 v209, v209, v192
	v_add_f32_e32 v201, v201, v209
	v_cndmask_b32_e64 v109, v101, v201, s[68:69]
	v_mul_f32_e32 v210, v210, v190
	v_mul_f32_e32 v202, v202, v102
	v_mul_f32_e32 v210, v210, v192
	v_add_f32_e32 v202, v202, v210
	v_cndmask_b32_e64 v110, v102, v202, s[68:69]
	v_mul_f32_e32 v211, v211, v191
	v_mul_f32_e32 v203, v203, v103
	v_mul_f32_e32 v211, v211, v192
	v_add_f32_e32 v203, v203, v211
	v_cndmask_b32_e64 v111, v103, v203, s[68:69]
	s_branch .LBB0_327

.LBB0_327:
	v_mov_b64_e32 v[100:101], s[78:79]
	v_mad_i64_i32 v[100:101], s[28:29], v112, s26, v[100:101]
	v_cvt_pk_bf16_f32 v96, v104, v105
	v_cvt_pk_bf16_f32 v97, v106, v107
	v_cvt_pk_bf16_f32 v98, v108, v109
	v_cvt_pk_bf16_f32 v99, v110, v111
	v_lshl_add_u64 v[100:101], v[160:161], 1, v[100:101]
	s_and_b64 vcc, exec, s[38:39]
	v_add_u32_e32 v104, 0x80, v181
	s_waitcnt lgkmcnt(0)
	s_add_u32 s68, s30, 0x42000
	s_addc_u32 s69, s31, 0
	global_store_dwordx4 v213, v[214:217], s[68:69] nt
	ds_bpermute_b32 v218, v212, v96
	ds_bpermute_b32 v219, v212, v97
	ds_bpermute_b32 v220, v212, v98
	ds_bpermute_b32 v221, v212, v99
	s_cbranch_vccnz .LBB0_377
	v_add_u32_e32 v182, 128, v181
	v_xor_b32_e32 v183, 16, v180
	v_and_b32_e32 v182, 0xfff, v182
	v_lshlrev_b32_e32 v183, 2, v183
	v_cvt_f32_u32_e32 v182, v182
	v_cmp_eq_u32_e64 s[60:61], 0, v171
	v_cmp_gt_u32_e64 s[68:69], 2, v171
	ds_bpermute_b32 v184, v183, v88
	ds_bpermute_b32 v185, v183, v89
	ds_bpermute_b32 v186, v183, v90
	ds_bpermute_b32 v187, v183, v91
	ds_bpermute_b32 v188, v183, v92
	ds_bpermute_b32 v189, v183, v93
	ds_bpermute_b32 v190, v183, v94
	ds_bpermute_b32 v191, v183, v95
	v_mov_b32_e32 v192, 1.0
	v_cndmask_b32_e64 v192, v192, -1.0, s[60:61]
	v_mul_f32_e32 v194, 0.15915494, v182
	v_rndne_f32_e32 v194, v194
	v_fma_f32 v194, v182, 0.15915494, -v194
	v_mul_f32_e32 v194, 0x40c90fdb, v194
	v_mul_f32_e32 v194, 0.15915494, v194
	v_sin_f32_e32 v204, v194
	v_cos_f32_e32 v196, v194
	v_mul_f32_e32 v193, 0x3e4693af, v182
	v_mul_f32_e32 v194, 0.15915494, v193
	v_rndne_f32_e32 v194, v194
	v_fma_f32 v194, v193, 0.15915494, -v194
	v_mul_f32_e32 v194, 0x40c90fdb, v194
	v_mul_f32_e32 v194, 0.15915494, v194
	v_sin_f32_e32 v205, v194
	v_cos_f32_e32 v197, v194
	v_mul_f32_e32 v193, 0x3d1a08c8, v182
	v_mul_f32_e32 v194, 0.15915494, v193
	v_rndne_f32_e32 v194, v194
	v_fma_f32 v194, v193, 0.15915494, -v194
	v_mul_f32_e32 v194, 0x40c90fdb, v194
	v_mul_f32_e32 v194, 0.15915494, v194
	v_sin_f32_e32 v206, v194
	v_cos_f32_e32 v198, v194
	v_mul_f32_e32 v193, 0x3beef74e, v182
	v_mul_f32_e32 v194, 0.15915494, v193
	v_rndne_f32_e32 v194, v194
	v_fma_f32 v194, v193, 0.15915494, -v194
	v_mul_f32_e32 v194, 0x40c90fdb, v194
	v_mul_f32_e32 v194, 0.15915494, v194
	v_sin_f32_e32 v207, v194
	v_cos_f32_e32 v199, v194
	v_mul_f32_e32 v193, 0x3ab95d22, v182
	v_mul_f32_e32 v194, 0.15915494, v193
	v_rndne_f32_e32 v194, v194
	v_fma_f32 v194, v193, 0.15915494, -v194
	v_mul_f32_e32 v194, 0x40c90fdb, v194
	v_mul_f32_e32 v194, 0.15915494, v194
	v_sin_f32_e32 v208, v194
	v_cos_f32_e32 v200, v194
	v_mul_f32_e32 v193, 0x398fc8f8, v182
	v_mul_f32_e32 v194, 0.15915494, v193
	v_rndne_f32_e32 v194, v194
	v_fma_f32 v194, v193, 0.15915494, -v194
	v_mul_f32_e32 v194, 0x40c90fdb, v194
	v_mul_f32_e32 v194, 0.15915494, v194
	v_sin_f32_e32 v209, v194
	v_cos_f32_e32 v201, v194
	v_mul_f32_e32 v193, 0x385f10c4, v182
	v_mul_f32_e32 v194, 0.15915494, v193
	v_rndne_f32_e32 v194, v194
	v_fma_f32 v194, v193, 0.15915494, -v194
	v_mul_f32_e32 v194, 0x40c90fdb, v194
	v_mul_f32_e32 v194, 0.15915494, v194
	v_sin_f32_e32 v210, v194
	v_cos_f32_e32 v202, v194
	v_mul_f32_e32 v193, 0x372d07a7, v182
	v_mul_f32_e32 v194, 0.15915494, v193
	v_rndne_f32_e32 v194, v194
	v_fma_f32 v194, v193, 0.15915494, -v194
	v_mul_f32_e32 v194, 0x40c90fdb, v194
	v_mul_f32_e32 v194, 0.15915494, v194
	v_sin_f32_e32 v211, v194
	v_cos_f32_e32 v203, v194
	s_waitcnt lgkmcnt(0)
	v_mul_f32_e32 v204, v204, v184
	v_mul_f32_e32 v196, v196, v88
	v_mul_f32_e32 v204, v204, v192
	v_add_f32_e32 v196, v196, v204
	v_cndmask_b32_e64 v96, v88, v196, s[68:69]
	v_mul_f32_e32 v205, v205, v185
	v_mul_f32_e32 v197, v197, v89
	v_mul_f32_e32 v205, v205, v192
	v_add_f32_e32 v197, v197, v205
	v_cndmask_b32_e64 v97, v89, v197, s[68:69]
	v_mul_f32_e32 v206, v206, v186
	v_mul_f32_e32 v198, v198, v90
	v_mul_f32_e32 v206, v206, v192
	v_add_f32_e32 v198, v198, v206
	v_cndmask_b32_e64 v98, v90, v198, s[68:69]
	v_mul_f32_e32 v207, v207, v187
	v_mul_f32_e32 v199, v199, v91
	v_mul_f32_e32 v207, v207, v192
	v_add_f32_e32 v199, v199, v207
	v_cndmask_b32_e64 v99, v91, v199, s[68:69]
	v_mul_f32_e32 v208, v208, v188
	v_mul_f32_e32 v200, v200, v92
	v_mul_f32_e32 v208, v208, v192
	v_add_f32_e32 v200, v200, v208
	v_cndmask_b32_e64 v100, v92, v200, s[68:69]
	v_mul_f32_e32 v209, v209, v189
	v_mul_f32_e32 v201, v201, v93
	v_mul_f32_e32 v209, v209, v192
	v_add_f32_e32 v201, v201, v209
	v_cndmask_b32_e64 v101, v93, v201, s[68:69]
	v_mul_f32_e32 v210, v210, v190
	v_mul_f32_e32 v202, v202, v94
	v_mul_f32_e32 v210, v210, v192
	v_add_f32_e32 v202, v202, v210
	v_cndmask_b32_e64 v102, v94, v202, s[68:69]
	v_mul_f32_e32 v211, v211, v191
	v_mul_f32_e32 v203, v203, v95
	v_mul_f32_e32 v211, v211, v192
	v_add_f32_e32 v203, v203, v211
	v_cndmask_b32_e64 v103, v95, v203, s[68:69]
	s_branch .LBB0_378

.LBB0_378:
	v_mov_b64_e32 v[92:93], s[78:79]
	v_mad_i64_i32 v[92:93], s[28:29], v104, s26, v[92:93]
	v_cvt_pk_bf16_f32 v88, v96, v97
	v_cvt_pk_bf16_f32 v89, v98, v99
	v_cvt_pk_bf16_f32 v90, v100, v101
	v_cvt_pk_bf16_f32 v91, v102, v103
	v_lshl_add_u64 v[92:93], v[160:161], 1, v[92:93]
	s_and_b64 vcc, exec, s[38:39]
	v_add_u32_e32 v96, 0x90, v181
	s_waitcnt lgkmcnt(0)
	s_add_u32 s68, s30, 0x63000
	s_addc_u32 s69, s31, 0
	global_store_dwordx4 v213, v[218:221], s[68:69] nt
	ds_bpermute_b32 v214, v212, v88
	ds_bpermute_b32 v215, v212, v89
	ds_bpermute_b32 v216, v212, v90
	ds_bpermute_b32 v217, v212, v91
	s_cbranch_vccnz .LBB0_428
	v_add_u32_e32 v182, 144, v181
	v_xor_b32_e32 v183, 16, v180
	v_and_b32_e32 v182, 0xfff, v182
	v_lshlrev_b32_e32 v183, 2, v183
	v_cvt_f32_u32_e32 v182, v182
	v_cmp_eq_u32_e64 s[60:61], 0, v171
	v_cmp_gt_u32_e64 s[68:69], 2, v171
	ds_bpermute_b32 v184, v183, v80
	ds_bpermute_b32 v185, v183, v81
	ds_bpermute_b32 v186, v183, v82
	ds_bpermute_b32 v187, v183, v83
	ds_bpermute_b32 v188, v183, v84
	ds_bpermute_b32 v189, v183, v85
	ds_bpermute_b32 v190, v183, v86
	ds_bpermute_b32 v191, v183, v87
	v_mov_b32_e32 v192, 1.0
	v_cndmask_b32_e64 v192, v192, -1.0, s[60:61]
	v_mul_f32_e32 v194, 0.15915494, v182
	v_rndne_f32_e32 v194, v194
	v_fma_f32 v194, v182, 0.15915494, -v194
	v_mul_f32_e32 v194, 0x40c90fdb, v194
	v_mul_f32_e32 v194, 0.15915494, v194
	v_sin_f32_e32 v204, v194
	v_cos_f32_e32 v196, v194
	v_mul_f32_e32 v193, 0x3e4693af, v182
	v_mul_f32_e32 v194, 0.15915494, v193
	v_rndne_f32_e32 v194, v194
	v_fma_f32 v194, v193, 0.15915494, -v194
	v_mul_f32_e32 v194, 0x40c90fdb, v194
	v_mul_f32_e32 v194, 0.15915494, v194
	v_sin_f32_e32 v205, v194
	v_cos_f32_e32 v197, v194
	v_mul_f32_e32 v193, 0x3d1a08c8, v182
	v_mul_f32_e32 v194, 0.15915494, v193
	v_rndne_f32_e32 v194, v194
	v_fma_f32 v194, v193, 0.15915494, -v194
	v_mul_f32_e32 v194, 0x40c90fdb, v194
	v_mul_f32_e32 v194, 0.15915494, v194
	v_sin_f32_e32 v206, v194
	v_cos_f32_e32 v198, v194
	v_mul_f32_e32 v193, 0x3beef74e, v182
	v_mul_f32_e32 v194, 0.15915494, v193
	v_rndne_f32_e32 v194, v194
	v_fma_f32 v194, v193, 0.15915494, -v194
	v_mul_f32_e32 v194, 0x40c90fdb, v194
	v_mul_f32_e32 v194, 0.15915494, v194
	v_sin_f32_e32 v207, v194
	v_cos_f32_e32 v199, v194
	v_mul_f32_e32 v193, 0x3ab95d22, v182
	v_mul_f32_e32 v194, 0.15915494, v193
	v_rndne_f32_e32 v194, v194
	v_fma_f32 v194, v193, 0.15915494, -v194
	v_mul_f32_e32 v194, 0x40c90fdb, v194
	v_mul_f32_e32 v194, 0.15915494, v194
	v_sin_f32_e32 v208, v194
	v_cos_f32_e32 v200, v194
	v_mul_f32_e32 v193, 0x398fc8f8, v182
	v_mul_f32_e32 v194, 0.15915494, v193
	v_rndne_f32_e32 v194, v194
	v_fma_f32 v194, v193, 0.15915494, -v194
	v_mul_f32_e32 v194, 0x40c90fdb, v194
	v_mul_f32_e32 v194, 0.15915494, v194
	v_sin_f32_e32 v209, v194
	v_cos_f32_e32 v201, v194
	v_mul_f32_e32 v193, 0x385f10c4, v182
	v_mul_f32_e32 v194, 0.15915494, v193
	v_rndne_f32_e32 v194, v194
	v_fma_f32 v194, v193, 0.15915494, -v194
	v_mul_f32_e32 v194, 0x40c90fdb, v194
	v_mul_f32_e32 v194, 0.15915494, v194
	v_sin_f32_e32 v210, v194
	v_cos_f32_e32 v202, v194
	v_mul_f32_e32 v193, 0x372d07a7, v182
	v_mul_f32_e32 v194, 0.15915494, v193
	v_rndne_f32_e32 v194, v194
	v_fma_f32 v194, v193, 0.15915494, -v194
	v_mul_f32_e32 v194, 0x40c90fdb, v194
	v_mul_f32_e32 v194, 0.15915494, v194
	v_sin_f32_e32 v211, v194
	v_cos_f32_e32 v203, v194
	s_waitcnt lgkmcnt(0)
	v_mul_f32_e32 v204, v204, v184
	v_mul_f32_e32 v196, v196, v80
	v_mul_f32_e32 v204, v204, v192
	v_add_f32_e32 v196, v196, v204
	v_cndmask_b32_e64 v88, v80, v196, s[68:69]
	v_mul_f32_e32 v205, v205, v185
	v_mul_f32_e32 v197, v197, v81
	v_mul_f32_e32 v205, v205, v192
	v_add_f32_e32 v197, v197, v205
	v_cndmask_b32_e64 v89, v81, v197, s[68:69]
	v_mul_f32_e32 v206, v206, v186
	v_mul_f32_e32 v198, v198, v82
	v_mul_f32_e32 v206, v206, v192
	v_add_f32_e32 v198, v198, v206
	v_cndmask_b32_e64 v90, v82, v198, s[68:69]
	v_mul_f32_e32 v207, v207, v187
	v_mul_f32_e32 v199, v199, v83
	v_mul_f32_e32 v207, v207, v192
	v_add_f32_e32 v199, v199, v207
	v_cndmask_b32_e64 v91, v83, v199, s[68:69]
	v_mul_f32_e32 v208, v208, v188
	v_mul_f32_e32 v200, v200, v84
	v_mul_f32_e32 v208, v208, v192
	v_add_f32_e32 v200, v200, v208
	v_cndmask_b32_e64 v92, v84, v200, s[68:69]
	v_mul_f32_e32 v209, v209, v189
	v_mul_f32_e32 v201, v201, v85
	v_mul_f32_e32 v209, v209, v192
	v_add_f32_e32 v201, v201, v209
	v_cndmask_b32_e64 v93, v85, v201, s[68:69]
	v_mul_f32_e32 v210, v210, v190
	v_mul_f32_e32 v202, v202, v86
	v_mul_f32_e32 v210, v210, v192
	v_add_f32_e32 v202, v202, v210
	v_cndmask_b32_e64 v94, v86, v202, s[68:69]
	v_mul_f32_e32 v211, v211, v191
	v_mul_f32_e32 v203, v203, v87
	v_mul_f32_e32 v211, v211, v192
	v_add_f32_e32 v203, v203, v211
	v_cndmask_b32_e64 v95, v87, v203, s[68:69]
	s_branch .LBB0_429

.LBB0_429:
	v_mov_b64_e32 v[84:85], s[78:79]
	v_mad_i64_i32 v[84:85], s[28:29], v96, s26, v[84:85]
	v_cvt_pk_bf16_f32 v80, v88, v89
	v_cvt_pk_bf16_f32 v81, v90, v91
	v_cvt_pk_bf16_f32 v82, v92, v93
	v_cvt_pk_bf16_f32 v83, v94, v95
	v_lshl_add_u64 v[84:85], v[160:161], 1, v[84:85]
	s_and_b64 vcc, exec, s[38:39]
	v_add_u32_e32 v88, 0xa0, v181
	s_waitcnt lgkmcnt(0)
	s_add_u32 s68, s30, 0x108000
	s_addc_u32 s69, s31, 0
	global_store_dwordx4 v213, v[214:217], s[68:69] nt
	ds_bpermute_b32 v218, v212, v80
	ds_bpermute_b32 v219, v212, v81
	ds_bpermute_b32 v220, v212, v82
	ds_bpermute_b32 v221, v212, v83
	s_cbranch_vccnz .LBB0_479
	v_add_u32_e32 v182, 160, v181
	v_xor_b32_e32 v183, 16, v180
	v_and_b32_e32 v182, 0xfff, v182
	v_lshlrev_b32_e32 v183, 2, v183
	v_cvt_f32_u32_e32 v182, v182
	v_cmp_eq_u32_e64 s[60:61], 0, v171
	v_cmp_gt_u32_e64 s[68:69], 2, v171
	ds_bpermute_b32 v184, v183, v72
	ds_bpermute_b32 v185, v183, v73
	ds_bpermute_b32 v186, v183, v74
	ds_bpermute_b32 v187, v183, v75
	ds_bpermute_b32 v188, v183, v76
	ds_bpermute_b32 v189, v183, v77
	ds_bpermute_b32 v190, v183, v78
	ds_bpermute_b32 v191, v183, v79
	v_mov_b32_e32 v192, 1.0
	v_cndmask_b32_e64 v192, v192, -1.0, s[60:61]
	v_mul_f32_e32 v194, 0.15915494, v182
	v_rndne_f32_e32 v194, v194
	v_fma_f32 v194, v182, 0.15915494, -v194
	v_mul_f32_e32 v194, 0x40c90fdb, v194
	v_mul_f32_e32 v194, 0.15915494, v194
	v_sin_f32_e32 v204, v194
	v_cos_f32_e32 v196, v194
	v_mul_f32_e32 v193, 0x3e4693af, v182
	v_mul_f32_e32 v194, 0.15915494, v193
	v_rndne_f32_e32 v194, v194
	v_fma_f32 v194, v193, 0.15915494, -v194
	v_mul_f32_e32 v194, 0x40c90fdb, v194
	v_mul_f32_e32 v194, 0.15915494, v194
	v_sin_f32_e32 v205, v194
	v_cos_f32_e32 v197, v194
	v_mul_f32_e32 v193, 0x3d1a08c8, v182
	v_mul_f32_e32 v194, 0.15915494, v193
	v_rndne_f32_e32 v194, v194
	v_fma_f32 v194, v193, 0.15915494, -v194
	v_mul_f32_e32 v194, 0x40c90fdb, v194
	v_mul_f32_e32 v194, 0.15915494, v194
	v_sin_f32_e32 v206, v194
	v_cos_f32_e32 v198, v194
	v_mul_f32_e32 v193, 0x3beef74e, v182
	v_mul_f32_e32 v194, 0.15915494, v193
	v_rndne_f32_e32 v194, v194
	v_fma_f32 v194, v193, 0.15915494, -v194
	v_mul_f32_e32 v194, 0x40c90fdb, v194
	v_mul_f32_e32 v194, 0.15915494, v194
	v_sin_f32_e32 v207, v194
	v_cos_f32_e32 v199, v194
	v_mul_f32_e32 v193, 0x3ab95d22, v182
	v_mul_f32_e32 v194, 0.15915494, v193
	v_rndne_f32_e32 v194, v194
	v_fma_f32 v194, v193, 0.15915494, -v194
	v_mul_f32_e32 v194, 0x40c90fdb, v194
	v_mul_f32_e32 v194, 0.15915494, v194
	v_sin_f32_e32 v208, v194
	v_cos_f32_e32 v200, v194
	v_mul_f32_e32 v193, 0x398fc8f8, v182
	v_mul_f32_e32 v194, 0.15915494, v193
	v_rndne_f32_e32 v194, v194
	v_fma_f32 v194, v193, 0.15915494, -v194
	v_mul_f32_e32 v194, 0x40c90fdb, v194
	v_mul_f32_e32 v194, 0.15915494, v194
	v_sin_f32_e32 v209, v194
	v_cos_f32_e32 v201, v194
	v_mul_f32_e32 v193, 0x385f10c4, v182
	v_mul_f32_e32 v194, 0.15915494, v193
	v_rndne_f32_e32 v194, v194
	v_fma_f32 v194, v193, 0.15915494, -v194
	v_mul_f32_e32 v194, 0x40c90fdb, v194
	v_mul_f32_e32 v194, 0.15915494, v194
	v_sin_f32_e32 v210, v194
	v_cos_f32_e32 v202, v194
	v_mul_f32_e32 v193, 0x372d07a7, v182
	v_mul_f32_e32 v194, 0.15915494, v193
	v_rndne_f32_e32 v194, v194
	v_fma_f32 v194, v193, 0.15915494, -v194
	v_mul_f32_e32 v194, 0x40c90fdb, v194
	v_mul_f32_e32 v194, 0.15915494, v194
	v_sin_f32_e32 v211, v194
	v_cos_f32_e32 v203, v194
	s_waitcnt lgkmcnt(0)
	v_mul_f32_e32 v204, v204, v184
	v_mul_f32_e32 v196, v196, v72
	v_mul_f32_e32 v204, v204, v192
	v_add_f32_e32 v196, v196, v204
	v_cndmask_b32_e64 v80, v72, v196, s[68:69]
	v_mul_f32_e32 v205, v205, v185
	v_mul_f32_e32 v197, v197, v73
	v_mul_f32_e32 v205, v205, v192
	v_add_f32_e32 v197, v197, v205
	v_cndmask_b32_e64 v81, v73, v197, s[68:69]
	v_mul_f32_e32 v206, v206, v186
	v_mul_f32_e32 v198, v198, v74
	v_mul_f32_e32 v206, v206, v192
	v_add_f32_e32 v198, v198, v206
	v_cndmask_b32_e64 v82, v74, v198, s[68:69]
	v_mul_f32_e32 v207, v207, v187
	v_mul_f32_e32 v199, v199, v75
	v_mul_f32_e32 v207, v207, v192
	v_add_f32_e32 v199, v199, v207
	v_cndmask_b32_e64 v83, v75, v199, s[68:69]
	v_mul_f32_e32 v208, v208, v188
	v_mul_f32_e32 v200, v200, v76
	v_mul_f32_e32 v208, v208, v192
	v_add_f32_e32 v200, v200, v208
	v_cndmask_b32_e64 v84, v76, v200, s[68:69]
	v_mul_f32_e32 v209, v209, v189
	v_mul_f32_e32 v201, v201, v77
	v_mul_f32_e32 v209, v209, v192
	v_add_f32_e32 v201, v201, v209
	v_cndmask_b32_e64 v85, v77, v201, s[68:69]
	v_mul_f32_e32 v210, v210, v190
	v_mul_f32_e32 v202, v202, v78
	v_mul_f32_e32 v210, v210, v192
	v_add_f32_e32 v202, v202, v210
	v_cndmask_b32_e64 v86, v78, v202, s[68:69]
	v_mul_f32_e32 v211, v211, v191
	v_mul_f32_e32 v203, v203, v79
	v_mul_f32_e32 v211, v211, v192
	v_add_f32_e32 v203, v203, v211
	v_cndmask_b32_e64 v87, v79, v203, s[68:69]
	s_branch .LBB0_480

.LBB0_480:
	v_mov_b64_e32 v[76:77], s[78:79]
	v_mad_i64_i32 v[76:77], s[28:29], v88, s26, v[76:77]
	v_cvt_pk_bf16_f32 v72, v80, v81
	v_cvt_pk_bf16_f32 v73, v82, v83
	v_cvt_pk_bf16_f32 v74, v84, v85
	v_cvt_pk_bf16_f32 v75, v86, v87
	v_lshl_add_u64 v[76:77], v[160:161], 1, v[76:77]
	s_and_b64 vcc, exec, s[38:39]
	v_add_u32_e32 v80, 0xb0, v181
	s_waitcnt lgkmcnt(0)
	s_add_u32 s68, s30, 0x129000
	s_addc_u32 s69, s31, 0
	global_store_dwordx4 v213, v[218:221], s[68:69] nt
	ds_bpermute_b32 v214, v212, v72
	ds_bpermute_b32 v215, v212, v73
	ds_bpermute_b32 v216, v212, v74
	ds_bpermute_b32 v217, v212, v75
	s_cbranch_vccnz .LBB0_530
	v_add_u32_e32 v182, 176, v181
	v_xor_b32_e32 v183, 16, v180
	v_and_b32_e32 v182, 0xfff, v182
	v_lshlrev_b32_e32 v183, 2, v183
	v_cvt_f32_u32_e32 v182, v182
	v_cmp_eq_u32_e64 s[60:61], 0, v171
	v_cmp_gt_u32_e64 s[68:69], 2, v171
	ds_bpermute_b32 v184, v183, v64
	ds_bpermute_b32 v185, v183, v65
	ds_bpermute_b32 v186, v183, v66
	ds_bpermute_b32 v187, v183, v67
	ds_bpermute_b32 v188, v183, v68
	ds_bpermute_b32 v189, v183, v69
	ds_bpermute_b32 v190, v183, v70
	ds_bpermute_b32 v191, v183, v71
	v_mov_b32_e32 v192, 1.0
	v_cndmask_b32_e64 v192, v192, -1.0, s[60:61]
	v_mul_f32_e32 v194, 0.15915494, v182
	v_rndne_f32_e32 v194, v194
	v_fma_f32 v194, v182, 0.15915494, -v194
	v_mul_f32_e32 v194, 0x40c90fdb, v194
	v_mul_f32_e32 v194, 0.15915494, v194
	v_sin_f32_e32 v204, v194
	v_cos_f32_e32 v196, v194
	v_mul_f32_e32 v193, 0x3e4693af, v182
	v_mul_f32_e32 v194, 0.15915494, v193
	v_rndne_f32_e32 v194, v194
	v_fma_f32 v194, v193, 0.15915494, -v194
	v_mul_f32_e32 v194, 0x40c90fdb, v194
	v_mul_f32_e32 v194, 0.15915494, v194
	v_sin_f32_e32 v205, v194
	v_cos_f32_e32 v197, v194
	v_mul_f32_e32 v193, 0x3d1a08c8, v182
	v_mul_f32_e32 v194, 0.15915494, v193
	v_rndne_f32_e32 v194, v194
	v_fma_f32 v194, v193, 0.15915494, -v194
	v_mul_f32_e32 v194, 0x40c90fdb, v194
	v_mul_f32_e32 v194, 0.15915494, v194
	v_sin_f32_e32 v206, v194
	v_cos_f32_e32 v198, v194
	v_mul_f32_e32 v193, 0x3beef74e, v182
	v_mul_f32_e32 v194, 0.15915494, v193
	v_rndne_f32_e32 v194, v194
	v_fma_f32 v194, v193, 0.15915494, -v194
	v_mul_f32_e32 v194, 0x40c90fdb, v194
	v_mul_f32_e32 v194, 0.15915494, v194
	v_sin_f32_e32 v207, v194
	v_cos_f32_e32 v199, v194
	v_mul_f32_e32 v193, 0x3ab95d22, v182
	v_mul_f32_e32 v194, 0.15915494, v193
	v_rndne_f32_e32 v194, v194
	v_fma_f32 v194, v193, 0.15915494, -v194
	v_mul_f32_e32 v194, 0x40c90fdb, v194
	v_mul_f32_e32 v194, 0.15915494, v194
	v_sin_f32_e32 v208, v194
	v_cos_f32_e32 v200, v194
	v_mul_f32_e32 v193, 0x398fc8f8, v182
	v_mul_f32_e32 v194, 0.15915494, v193
	v_rndne_f32_e32 v194, v194
	v_fma_f32 v194, v193, 0.15915494, -v194
	v_mul_f32_e32 v194, 0x40c90fdb, v194
	v_mul_f32_e32 v194, 0.15915494, v194
	v_sin_f32_e32 v209, v194
	v_cos_f32_e32 v201, v194
	v_mul_f32_e32 v193, 0x385f10c4, v182
	v_mul_f32_e32 v194, 0.15915494, v193
	v_rndne_f32_e32 v194, v194
	v_fma_f32 v194, v193, 0.15915494, -v194
	v_mul_f32_e32 v194, 0x40c90fdb, v194
	v_mul_f32_e32 v194, 0.15915494, v194
	v_sin_f32_e32 v210, v194
	v_cos_f32_e32 v202, v194
	v_mul_f32_e32 v193, 0x372d07a7, v182
	v_mul_f32_e32 v194, 0.15915494, v193
	v_rndne_f32_e32 v194, v194
	v_fma_f32 v194, v193, 0.15915494, -v194
	v_mul_f32_e32 v194, 0x40c90fdb, v194
	v_mul_f32_e32 v194, 0.15915494, v194
	v_sin_f32_e32 v211, v194
	v_cos_f32_e32 v203, v194
	s_waitcnt lgkmcnt(0)
	v_mul_f32_e32 v204, v204, v184
	v_mul_f32_e32 v196, v196, v64
	v_mul_f32_e32 v204, v204, v192
	v_add_f32_e32 v196, v196, v204
	v_cndmask_b32_e64 v72, v64, v196, s[68:69]
	v_mul_f32_e32 v205, v205, v185
	v_mul_f32_e32 v197, v197, v65
	v_mul_f32_e32 v205, v205, v192
	v_add_f32_e32 v197, v197, v205
	v_cndmask_b32_e64 v73, v65, v197, s[68:69]
	v_mul_f32_e32 v206, v206, v186
	v_mul_f32_e32 v198, v198, v66
	v_mul_f32_e32 v206, v206, v192
	v_add_f32_e32 v198, v198, v206
	v_cndmask_b32_e64 v74, v66, v198, s[68:69]
	v_mul_f32_e32 v207, v207, v187
	v_mul_f32_e32 v199, v199, v67
	v_mul_f32_e32 v207, v207, v192
	v_add_f32_e32 v199, v199, v207
	v_cndmask_b32_e64 v75, v67, v199, s[68:69]
	v_mul_f32_e32 v208, v208, v188
	v_mul_f32_e32 v200, v200, v68
	v_mul_f32_e32 v208, v208, v192
	v_add_f32_e32 v200, v200, v208
	v_cndmask_b32_e64 v76, v68, v200, s[68:69]
	v_mul_f32_e32 v209, v209, v189
	v_mul_f32_e32 v201, v201, v69
	v_mul_f32_e32 v209, v209, v192
	v_add_f32_e32 v201, v201, v209
	v_cndmask_b32_e64 v77, v69, v201, s[68:69]
	v_mul_f32_e32 v210, v210, v190
	v_mul_f32_e32 v202, v202, v70
	v_mul_f32_e32 v210, v210, v192
	v_add_f32_e32 v202, v202, v210
	v_cndmask_b32_e64 v78, v70, v202, s[68:69]
	v_mul_f32_e32 v211, v211, v191
	v_mul_f32_e32 v203, v203, v71
	v_mul_f32_e32 v211, v211, v192
	v_add_f32_e32 v203, v203, v211
	v_cndmask_b32_e64 v79, v71, v203, s[68:69]
	s_branch .LBB0_531

.LBB0_531:
	v_mov_b64_e32 v[68:69], s[78:79]
	v_mad_i64_i32 v[68:69], s[28:29], v80, s26, v[68:69]
	v_cvt_pk_bf16_f32 v64, v72, v73
	v_cvt_pk_bf16_f32 v65, v74, v75
	v_cvt_pk_bf16_f32 v66, v76, v77
	v_cvt_pk_bf16_f32 v67, v78, v79
	v_lshl_add_u64 v[68:69], v[160:161], 1, v[68:69]
	s_waitcnt lgkmcnt(0)
	s_add_u32 s68, s30, 0x14a000
	s_addc_u32 s69, s31, 0
	global_store_dwordx4 v213, v[214:217], s[68:69] nt
	ds_bpermute_b32 v218, v212, v64
	ds_bpermute_b32 v219, v212, v65
	ds_bpermute_b32 v220, v212, v66
	ds_bpermute_b32 v221, v212, v67
	s_waitcnt lgkmcnt(0)
	s_add_u32 s68, s30, 0x16b000
	s_addc_u32 s69, s31, 0
	global_store_dwordx4 v213, v[218:221], s[68:69] nt
	s_or_b32 s28, s54, 0x80
	s_cmpk_gt_i32 s28, 0x107f
	s_cbranch_scc1 .LBB0_122

.LBB0_583:
	v_mov_b64_e32 v[60:61], s[78:79]
	s_ashr_i32 s55, s54, 31
	v_cvt_pk_bf16_f32 v56, v64, v65
	v_mad_i64_i32 v[60:61], s[28:29], v181, s26, v[60:61]
	v_lshl_add_u64 v[64:65], s[54:55], 0, v[150:151]
	v_cvt_pk_bf16_f32 v57, v66, v67
	v_cvt_pk_bf16_f32 v58, v68, v69
	v_cvt_pk_bf16_f32 v59, v70, v71
	v_lshl_add_u64 v[60:61], v[64:65], 1, v[60:61]
	s_and_b64 vcc, exec, s[38:39]
	v_or_b32_e32 v66, 16, v181
	ds_bpermute_b32 v214, v212, v56
	ds_bpermute_b32 v215, v212, v57
	ds_bpermute_b32 v216, v212, v58
	ds_bpermute_b32 v217, v212, v59
	s_cbranch_vccnz .LBB0_633
	v_add_u32_e32 v182, 16, v181
	v_xor_b32_e32 v183, 16, v180
	v_and_b32_e32 v182, 0xfff, v182
	v_lshlrev_b32_e32 v183, 2, v183
	v_cvt_f32_u32_e32 v182, v182
	v_cmp_eq_u32_e64 s[60:61], 0, v171
	v_cmp_gt_u32_e64 s[68:69], 2, v171
	ds_bpermute_b32 v184, v183, v48
	ds_bpermute_b32 v185, v183, v49
	ds_bpermute_b32 v186, v183, v50
	ds_bpermute_b32 v187, v183, v51
	ds_bpermute_b32 v188, v183, v52
	ds_bpermute_b32 v189, v183, v53
	ds_bpermute_b32 v190, v183, v54
	ds_bpermute_b32 v191, v183, v55
	v_mov_b32_e32 v192, 1.0
	v_cndmask_b32_e64 v192, v192, -1.0, s[60:61]
	v_mul_f32_e32 v194, 0.15915494, v182
	v_rndne_f32_e32 v194, v194
	v_fma_f32 v194, v182, 0.15915494, -v194
	v_mul_f32_e32 v194, 0x40c90fdb, v194
	v_mul_f32_e32 v194, 0.15915494, v194
	v_sin_f32_e32 v204, v194
	v_cos_f32_e32 v196, v194
	v_mul_f32_e32 v193, 0x3e4693af, v182
	v_mul_f32_e32 v194, 0.15915494, v193
	v_rndne_f32_e32 v194, v194
	v_fma_f32 v194, v193, 0.15915494, -v194
	v_mul_f32_e32 v194, 0x40c90fdb, v194
	v_mul_f32_e32 v194, 0.15915494, v194
	v_sin_f32_e32 v205, v194
	v_cos_f32_e32 v197, v194
	v_mul_f32_e32 v193, 0x3d1a08c8, v182
	v_mul_f32_e32 v194, 0.15915494, v193
	v_rndne_f32_e32 v194, v194
	v_fma_f32 v194, v193, 0.15915494, -v194
	v_mul_f32_e32 v194, 0x40c90fdb, v194
	v_mul_f32_e32 v194, 0.15915494, v194
	v_sin_f32_e32 v206, v194
	v_cos_f32_e32 v198, v194
	v_mul_f32_e32 v193, 0x3beef74e, v182
	v_mul_f32_e32 v194, 0.15915494, v193
	v_rndne_f32_e32 v194, v194
	v_fma_f32 v194, v193, 0.15915494, -v194
	v_mul_f32_e32 v194, 0x40c90fdb, v194
	v_mul_f32_e32 v194, 0.15915494, v194
	v_sin_f32_e32 v207, v194
	v_cos_f32_e32 v199, v194
	v_mul_f32_e32 v193, 0x3ab95d22, v182
	v_mul_f32_e32 v194, 0.15915494, v193
	v_rndne_f32_e32 v194, v194
	v_fma_f32 v194, v193, 0.15915494, -v194
	v_mul_f32_e32 v194, 0x40c90fdb, v194
	v_mul_f32_e32 v194, 0.15915494, v194
	v_sin_f32_e32 v208, v194
	v_cos_f32_e32 v200, v194
	v_mul_f32_e32 v193, 0x398fc8f8, v182
	v_mul_f32_e32 v194, 0.15915494, v193
	v_rndne_f32_e32 v194, v194
	v_fma_f32 v194, v193, 0.15915494, -v194
	v_mul_f32_e32 v194, 0x40c90fdb, v194
	v_mul_f32_e32 v194, 0.15915494, v194
	v_sin_f32_e32 v209, v194
	v_cos_f32_e32 v201, v194
	v_mul_f32_e32 v193, 0x385f10c4, v182
	v_mul_f32_e32 v194, 0.15915494, v193
	v_rndne_f32_e32 v194, v194
	v_fma_f32 v194, v193, 0.15915494, -v194
	v_mul_f32_e32 v194, 0x40c90fdb, v194
	v_mul_f32_e32 v194, 0.15915494, v194
	v_sin_f32_e32 v210, v194
	v_cos_f32_e32 v202, v194
	v_mul_f32_e32 v193, 0x372d07a7, v182
	v_mul_f32_e32 v194, 0.15915494, v193
	v_rndne_f32_e32 v194, v194
	v_fma_f32 v194, v193, 0.15915494, -v194
	v_mul_f32_e32 v194, 0x40c90fdb, v194
	v_mul_f32_e32 v194, 0.15915494, v194
	v_sin_f32_e32 v211, v194
	v_cos_f32_e32 v203, v194
	s_waitcnt lgkmcnt(0)
	v_mul_f32_e32 v204, v204, v184
	v_mul_f32_e32 v196, v196, v48
	v_mul_f32_e32 v204, v204, v192
	v_add_f32_e32 v196, v196, v204
	v_cndmask_b32_e64 v56, v48, v196, s[68:69]
	v_mul_f32_e32 v205, v205, v185
	v_mul_f32_e32 v197, v197, v49
	v_mul_f32_e32 v205, v205, v192
	v_add_f32_e32 v197, v197, v205
	v_cndmask_b32_e64 v57, v49, v197, s[68:69]
	v_mul_f32_e32 v206, v206, v186
	v_mul_f32_e32 v198, v198, v50
	v_mul_f32_e32 v206, v206, v192
	v_add_f32_e32 v198, v198, v206
	v_cndmask_b32_e64 v58, v50, v198, s[68:69]
	v_mul_f32_e32 v207, v207, v187
	v_mul_f32_e32 v199, v199, v51
	v_mul_f32_e32 v207, v207, v192
	v_add_f32_e32 v199, v199, v207
	v_cndmask_b32_e64 v59, v51, v199, s[68:69]
	v_mul_f32_e32 v208, v208, v188
	v_mul_f32_e32 v200, v200, v52
	v_mul_f32_e32 v208, v208, v192
	v_add_f32_e32 v200, v200, v208
	v_cndmask_b32_e64 v60, v52, v200, s[68:69]
	v_mul_f32_e32 v209, v209, v189
	v_mul_f32_e32 v201, v201, v53
	v_mul_f32_e32 v209, v209, v192
	v_add_f32_e32 v201, v201, v209
	v_cndmask_b32_e64 v61, v53, v201, s[68:69]
	v_mul_f32_e32 v210, v210, v190
	v_mul_f32_e32 v202, v202, v54
	v_mul_f32_e32 v210, v210, v192
	v_add_f32_e32 v202, v202, v210
	v_cndmask_b32_e64 v62, v54, v202, s[68:69]
	v_mul_f32_e32 v211, v211, v191
	v_mul_f32_e32 v203, v203, v55
	v_mul_f32_e32 v211, v211, v192
	v_add_f32_e32 v203, v203, v211
	v_cndmask_b32_e64 v63, v55, v203, s[68:69]
	s_branch .LBB0_634

.LBB0_634:
	v_mov_b64_e32 v[52:53], s[78:79]
	v_mad_i64_i32 v[52:53], s[28:29], v66, s26, v[52:53]
	v_cvt_pk_bf16_f32 v48, v56, v57
	v_cvt_pk_bf16_f32 v49, v58, v59
	v_cvt_pk_bf16_f32 v50, v60, v61
	v_cvt_pk_bf16_f32 v51, v62, v63
	v_lshl_add_u64 v[52:53], v[64:65], 1, v[52:53]
	s_and_b64 vcc, exec, s[38:39]
	v_or_b32_e32 v56, 32, v181
	s_waitcnt lgkmcnt(0)
	s_add_u32 s68, s30, 0x100
	s_addc_u32 s69, s31, 0
	global_store_dwordx4 v213, v[214:217], s[68:69] nt
	ds_bpermute_b32 v218, v212, v48
	ds_bpermute_b32 v219, v212, v49
	ds_bpermute_b32 v220, v212, v50
	ds_bpermute_b32 v221, v212, v51
	s_cbranch_vccnz .LBB0_684
	v_add_u32_e32 v182, 32, v181
	v_xor_b32_e32 v183, 16, v180
	v_and_b32_e32 v182, 0xfff, v182
	v_lshlrev_b32_e32 v183, 2, v183
	v_cvt_f32_u32_e32 v182, v182
	v_cmp_eq_u32_e64 s[60:61], 0, v171
	v_cmp_gt_u32_e64 s[68:69], 2, v171
	ds_bpermute_b32 v184, v183, v40
	ds_bpermute_b32 v185, v183, v41
	ds_bpermute_b32 v186, v183, v42
	ds_bpermute_b32 v187, v183, v43
	ds_bpermute_b32 v188, v183, v44
	ds_bpermute_b32 v189, v183, v45
	ds_bpermute_b32 v190, v183, v46
	ds_bpermute_b32 v191, v183, v47
	v_mov_b32_e32 v192, 1.0
	v_cndmask_b32_e64 v192, v192, -1.0, s[60:61]
	v_mul_f32_e32 v194, 0.15915494, v182
	v_rndne_f32_e32 v194, v194
	v_fma_f32 v194, v182, 0.15915494, -v194
	v_mul_f32_e32 v194, 0x40c90fdb, v194
	v_mul_f32_e32 v194, 0.15915494, v194
	v_sin_f32_e32 v204, v194
	v_cos_f32_e32 v196, v194
	v_mul_f32_e32 v193, 0x3e4693af, v182
	v_mul_f32_e32 v194, 0.15915494, v193
	v_rndne_f32_e32 v194, v194
	v_fma_f32 v194, v193, 0.15915494, -v194
	v_mul_f32_e32 v194, 0x40c90fdb, v194
	v_mul_f32_e32 v194, 0.15915494, v194
	v_sin_f32_e32 v205, v194
	v_cos_f32_e32 v197, v194
	v_mul_f32_e32 v193, 0x3d1a08c8, v182
	v_mul_f32_e32 v194, 0.15915494, v193
	v_rndne_f32_e32 v194, v194
	v_fma_f32 v194, v193, 0.15915494, -v194
	v_mul_f32_e32 v194, 0x40c90fdb, v194
	v_mul_f32_e32 v194, 0.15915494, v194
	v_sin_f32_e32 v206, v194
	v_cos_f32_e32 v198, v194
	v_mul_f32_e32 v193, 0x3beef74e, v182
	v_mul_f32_e32 v194, 0.15915494, v193
	v_rndne_f32_e32 v194, v194
	v_fma_f32 v194, v193, 0.15915494, -v194
	v_mul_f32_e32 v194, 0x40c90fdb, v194
	v_mul_f32_e32 v194, 0.15915494, v194
	v_sin_f32_e32 v207, v194
	v_cos_f32_e32 v199, v194
	v_mul_f32_e32 v193, 0x3ab95d22, v182
	v_mul_f32_e32 v194, 0.15915494, v193
	v_rndne_f32_e32 v194, v194
	v_fma_f32 v194, v193, 0.15915494, -v194
	v_mul_f32_e32 v194, 0x40c90fdb, v194
	v_mul_f32_e32 v194, 0.15915494, v194
	v_sin_f32_e32 v208, v194
	v_cos_f32_e32 v200, v194
	v_mul_f32_e32 v193, 0x398fc8f8, v182
	v_mul_f32_e32 v194, 0.15915494, v193
	v_rndne_f32_e32 v194, v194
	v_fma_f32 v194, v193, 0.15915494, -v194
	v_mul_f32_e32 v194, 0x40c90fdb, v194
	v_mul_f32_e32 v194, 0.15915494, v194
	v_sin_f32_e32 v209, v194
	v_cos_f32_e32 v201, v194
	v_mul_f32_e32 v193, 0x385f10c4, v182
	v_mul_f32_e32 v194, 0.15915494, v193
	v_rndne_f32_e32 v194, v194
	v_fma_f32 v194, v193, 0.15915494, -v194
	v_mul_f32_e32 v194, 0x40c90fdb, v194
	v_mul_f32_e32 v194, 0.15915494, v194
	v_sin_f32_e32 v210, v194
	v_cos_f32_e32 v202, v194
	v_mul_f32_e32 v193, 0x372d07a7, v182
	v_mul_f32_e32 v194, 0.15915494, v193
	v_rndne_f32_e32 v194, v194
	v_fma_f32 v194, v193, 0.15915494, -v194
	v_mul_f32_e32 v194, 0x40c90fdb, v194
	v_mul_f32_e32 v194, 0.15915494, v194
	v_sin_f32_e32 v211, v194
	v_cos_f32_e32 v203, v194
	s_waitcnt lgkmcnt(0)
	v_mul_f32_e32 v204, v204, v184
	v_mul_f32_e32 v196, v196, v40
	v_mul_f32_e32 v204, v204, v192
	v_add_f32_e32 v196, v196, v204
	v_cndmask_b32_e64 v48, v40, v196, s[68:69]
	v_mul_f32_e32 v205, v205, v185
	v_mul_f32_e32 v197, v197, v41
	v_mul_f32_e32 v205, v205, v192
	v_add_f32_e32 v197, v197, v205
	v_cndmask_b32_e64 v49, v41, v197, s[68:69]
	v_mul_f32_e32 v206, v206, v186
	v_mul_f32_e32 v198, v198, v42
	v_mul_f32_e32 v206, v206, v192
	v_add_f32_e32 v198, v198, v206
	v_cndmask_b32_e64 v50, v42, v198, s[68:69]
	v_mul_f32_e32 v207, v207, v187
	v_mul_f32_e32 v199, v199, v43
	v_mul_f32_e32 v207, v207, v192
	v_add_f32_e32 v199, v199, v207
	v_cndmask_b32_e64 v51, v43, v199, s[68:69]
	v_mul_f32_e32 v208, v208, v188
	v_mul_f32_e32 v200, v200, v44
	v_mul_f32_e32 v208, v208, v192
	v_add_f32_e32 v200, v200, v208
	v_cndmask_b32_e64 v52, v44, v200, s[68:69]
	v_mul_f32_e32 v209, v209, v189
	v_mul_f32_e32 v201, v201, v45
	v_mul_f32_e32 v209, v209, v192
	v_add_f32_e32 v201, v201, v209
	v_cndmask_b32_e64 v53, v45, v201, s[68:69]
	v_mul_f32_e32 v210, v210, v190
	v_mul_f32_e32 v202, v202, v46
	v_mul_f32_e32 v210, v210, v192
	v_add_f32_e32 v202, v202, v210
	v_cndmask_b32_e64 v54, v46, v202, s[68:69]
	v_mul_f32_e32 v211, v211, v191
	v_mul_f32_e32 v203, v203, v47
	v_mul_f32_e32 v211, v211, v192
	v_add_f32_e32 v203, v203, v211
	v_cndmask_b32_e64 v55, v47, v203, s[68:69]
	s_branch .LBB0_685

.LBB0_685:
	v_mov_b64_e32 v[44:45], s[78:79]
	v_mad_i64_i32 v[44:45], s[28:29], v56, s26, v[44:45]
	v_cvt_pk_bf16_f32 v40, v48, v49
	v_cvt_pk_bf16_f32 v41, v50, v51
	v_cvt_pk_bf16_f32 v42, v52, v53
	v_cvt_pk_bf16_f32 v43, v54, v55
	v_lshl_add_u64 v[44:45], v[64:65], 1, v[44:45]
	s_and_b64 vcc, exec, s[38:39]
	v_or_b32_e32 v48, 48, v181
	s_waitcnt lgkmcnt(0)
	s_add_u32 s68, s30, 0x21100
	s_addc_u32 s69, s31, 0
	global_store_dwordx4 v213, v[218:221], s[68:69] nt
	ds_bpermute_b32 v214, v212, v40
	ds_bpermute_b32 v215, v212, v41
	ds_bpermute_b32 v216, v212, v42
	ds_bpermute_b32 v217, v212, v43
	s_cbranch_vccnz .LBB0_735
	v_add_u32_e32 v182, 48, v181
	v_xor_b32_e32 v183, 16, v180
	v_and_b32_e32 v182, 0xfff, v182
	v_lshlrev_b32_e32 v183, 2, v183
	v_cvt_f32_u32_e32 v182, v182
	v_cmp_eq_u32_e64 s[60:61], 0, v171
	v_cmp_gt_u32_e64 s[68:69], 2, v171
	ds_bpermute_b32 v184, v183, v32
	ds_bpermute_b32 v185, v183, v33
	ds_bpermute_b32 v186, v183, v34
	ds_bpermute_b32 v187, v183, v35
	ds_bpermute_b32 v188, v183, v36
	ds_bpermute_b32 v189, v183, v37
	ds_bpermute_b32 v190, v183, v38
	ds_bpermute_b32 v191, v183, v39
	v_mov_b32_e32 v192, 1.0
	v_cndmask_b32_e64 v192, v192, -1.0, s[60:61]
	v_mul_f32_e32 v194, 0.15915494, v182
	v_rndne_f32_e32 v194, v194
	v_fma_f32 v194, v182, 0.15915494, -v194
	v_mul_f32_e32 v194, 0x40c90fdb, v194
	v_mul_f32_e32 v194, 0.15915494, v194
	v_sin_f32_e32 v204, v194
	v_cos_f32_e32 v196, v194
	v_mul_f32_e32 v193, 0x3e4693af, v182
	v_mul_f32_e32 v194, 0.15915494, v193
	v_rndne_f32_e32 v194, v194
	v_fma_f32 v194, v193, 0.15915494, -v194
	v_mul_f32_e32 v194, 0x40c90fdb, v194
	v_mul_f32_e32 v194, 0.15915494, v194
	v_sin_f32_e32 v205, v194
	v_cos_f32_e32 v197, v194
	v_mul_f32_e32 v193, 0x3d1a08c8, v182
	v_mul_f32_e32 v194, 0.15915494, v193
	v_rndne_f32_e32 v194, v194
	v_fma_f32 v194, v193, 0.15915494, -v194
	v_mul_f32_e32 v194, 0x40c90fdb, v194
	v_mul_f32_e32 v194, 0.15915494, v194
	v_sin_f32_e32 v206, v194
	v_cos_f32_e32 v198, v194
	v_mul_f32_e32 v193, 0x3beef74e, v182
	v_mul_f32_e32 v194, 0.15915494, v193
	v_rndne_f32_e32 v194, v194
	v_fma_f32 v194, v193, 0.15915494, -v194
	v_mul_f32_e32 v194, 0x40c90fdb, v194
	v_mul_f32_e32 v194, 0.15915494, v194
	v_sin_f32_e32 v207, v194
	v_cos_f32_e32 v199, v194
	v_mul_f32_e32 v193, 0x3ab95d22, v182
	v_mul_f32_e32 v194, 0.15915494, v193
	v_rndne_f32_e32 v194, v194
	v_fma_f32 v194, v193, 0.15915494, -v194
	v_mul_f32_e32 v194, 0x40c90fdb, v194
	v_mul_f32_e32 v194, 0.15915494, v194
	v_sin_f32_e32 v208, v194
	v_cos_f32_e32 v200, v194
	v_mul_f32_e32 v193, 0x398fc8f8, v182
	v_mul_f32_e32 v194, 0.15915494, v193
	v_rndne_f32_e32 v194, v194
	v_fma_f32 v194, v193, 0.15915494, -v194
	v_mul_f32_e32 v194, 0x40c90fdb, v194
	v_mul_f32_e32 v194, 0.15915494, v194
	v_sin_f32_e32 v209, v194
	v_cos_f32_e32 v201, v194
	v_mul_f32_e32 v193, 0x385f10c4, v182
	v_mul_f32_e32 v194, 0.15915494, v193
	v_rndne_f32_e32 v194, v194
	v_fma_f32 v194, v193, 0.15915494, -v194
	v_mul_f32_e32 v194, 0x40c90fdb, v194
	v_mul_f32_e32 v194, 0.15915494, v194
	v_sin_f32_e32 v210, v194
	v_cos_f32_e32 v202, v194
	v_mul_f32_e32 v193, 0x372d07a7, v182
	v_mul_f32_e32 v194, 0.15915494, v193
	v_rndne_f32_e32 v194, v194
	v_fma_f32 v194, v193, 0.15915494, -v194
	v_mul_f32_e32 v194, 0x40c90fdb, v194
	v_mul_f32_e32 v194, 0.15915494, v194
	v_sin_f32_e32 v211, v194
	v_cos_f32_e32 v203, v194
	s_waitcnt lgkmcnt(0)
	v_mul_f32_e32 v204, v204, v184
	v_mul_f32_e32 v196, v196, v32
	v_mul_f32_e32 v204, v204, v192
	v_add_f32_e32 v196, v196, v204
	v_cndmask_b32_e64 v40, v32, v196, s[68:69]
	v_mul_f32_e32 v205, v205, v185
	v_mul_f32_e32 v197, v197, v33
	v_mul_f32_e32 v205, v205, v192
	v_add_f32_e32 v197, v197, v205
	v_cndmask_b32_e64 v41, v33, v197, s[68:69]
	v_mul_f32_e32 v206, v206, v186
	v_mul_f32_e32 v198, v198, v34
	v_mul_f32_e32 v206, v206, v192
	v_add_f32_e32 v198, v198, v206
	v_cndmask_b32_e64 v42, v34, v198, s[68:69]
	v_mul_f32_e32 v207, v207, v187
	v_mul_f32_e32 v199, v199, v35
	v_mul_f32_e32 v207, v207, v192
	v_add_f32_e32 v199, v199, v207
	v_cndmask_b32_e64 v43, v35, v199, s[68:69]
	v_mul_f32_e32 v208, v208, v188
	v_mul_f32_e32 v200, v200, v36
	v_mul_f32_e32 v208, v208, v192
	v_add_f32_e32 v200, v200, v208
	v_cndmask_b32_e64 v44, v36, v200, s[68:69]
	v_mul_f32_e32 v209, v209, v189
	v_mul_f32_e32 v201, v201, v37
	v_mul_f32_e32 v209, v209, v192
	v_add_f32_e32 v201, v201, v209
	v_cndmask_b32_e64 v45, v37, v201, s[68:69]
	v_mul_f32_e32 v210, v210, v190
	v_mul_f32_e32 v202, v202, v38
	v_mul_f32_e32 v210, v210, v192
	v_add_f32_e32 v202, v202, v210
	v_cndmask_b32_e64 v46, v38, v202, s[68:69]
	v_mul_f32_e32 v211, v211, v191
	v_mul_f32_e32 v203, v203, v39
	v_mul_f32_e32 v211, v211, v192
	v_add_f32_e32 v203, v203, v211
	v_cndmask_b32_e64 v47, v39, v203, s[68:69]
	s_branch .LBB0_736

.LBB0_736:
	v_mov_b64_e32 v[36:37], s[78:79]
	v_mad_i64_i32 v[36:37], s[28:29], v48, s26, v[36:37]
	v_cvt_pk_bf16_f32 v32, v40, v41
	v_cvt_pk_bf16_f32 v33, v42, v43
	v_cvt_pk_bf16_f32 v34, v44, v45
	v_cvt_pk_bf16_f32 v35, v46, v47
	v_lshl_add_u64 v[36:37], v[64:65], 1, v[36:37]
	s_and_b64 vcc, exec, s[38:39]
	v_add_u32_e32 v40, 0x80, v181
	s_waitcnt lgkmcnt(0)
	s_add_u32 s68, s30, 0x42100
	s_addc_u32 s69, s31, 0
	global_store_dwordx4 v213, v[214:217], s[68:69] nt
	ds_bpermute_b32 v218, v212, v32
	ds_bpermute_b32 v219, v212, v33
	ds_bpermute_b32 v220, v212, v34
	ds_bpermute_b32 v221, v212, v35
	s_cbranch_vccnz .LBB0_786
	v_add_u32_e32 v182, 128, v181
	v_xor_b32_e32 v183, 16, v180
	v_and_b32_e32 v182, 0xfff, v182
	v_lshlrev_b32_e32 v183, 2, v183
	v_cvt_f32_u32_e32 v182, v182
	v_cmp_eq_u32_e64 s[60:61], 0, v171
	v_cmp_gt_u32_e64 s[68:69], 2, v171
	ds_bpermute_b32 v184, v183, v24
	ds_bpermute_b32 v185, v183, v25
	ds_bpermute_b32 v186, v183, v26
	ds_bpermute_b32 v187, v183, v27
	ds_bpermute_b32 v188, v183, v28
	ds_bpermute_b32 v189, v183, v29
	ds_bpermute_b32 v190, v183, v30
	ds_bpermute_b32 v191, v183, v31
	v_mov_b32_e32 v192, 1.0
	v_cndmask_b32_e64 v192, v192, -1.0, s[60:61]
	v_mul_f32_e32 v194, 0.15915494, v182
	v_rndne_f32_e32 v194, v194
	v_fma_f32 v194, v182, 0.15915494, -v194
	v_mul_f32_e32 v194, 0x40c90fdb, v194
	v_mul_f32_e32 v194, 0.15915494, v194
	v_sin_f32_e32 v204, v194
	v_cos_f32_e32 v196, v194
	v_mul_f32_e32 v193, 0x3e4693af, v182
	v_mul_f32_e32 v194, 0.15915494, v193
	v_rndne_f32_e32 v194, v194
	v_fma_f32 v194, v193, 0.15915494, -v194
	v_mul_f32_e32 v194, 0x40c90fdb, v194
	v_mul_f32_e32 v194, 0.15915494, v194
	v_sin_f32_e32 v205, v194
	v_cos_f32_e32 v197, v194
	v_mul_f32_e32 v193, 0x3d1a08c8, v182
	v_mul_f32_e32 v194, 0.15915494, v193
	v_rndne_f32_e32 v194, v194
	v_fma_f32 v194, v193, 0.15915494, -v194
	v_mul_f32_e32 v194, 0x40c90fdb, v194
	v_mul_f32_e32 v194, 0.15915494, v194
	v_sin_f32_e32 v206, v194
	v_cos_f32_e32 v198, v194
	v_mul_f32_e32 v193, 0x3beef74e, v182
	v_mul_f32_e32 v194, 0.15915494, v193
	v_rndne_f32_e32 v194, v194
	v_fma_f32 v194, v193, 0.15915494, -v194
	v_mul_f32_e32 v194, 0x40c90fdb, v194
	v_mul_f32_e32 v194, 0.15915494, v194
	v_sin_f32_e32 v207, v194
	v_cos_f32_e32 v199, v194
	v_mul_f32_e32 v193, 0x3ab95d22, v182
	v_mul_f32_e32 v194, 0.15915494, v193
	v_rndne_f32_e32 v194, v194
	v_fma_f32 v194, v193, 0.15915494, -v194
	v_mul_f32_e32 v194, 0x40c90fdb, v194
	v_mul_f32_e32 v194, 0.15915494, v194
	v_sin_f32_e32 v208, v194
	v_cos_f32_e32 v200, v194
	v_mul_f32_e32 v193, 0x398fc8f8, v182
	v_mul_f32_e32 v194, 0.15915494, v193
	v_rndne_f32_e32 v194, v194
	v_fma_f32 v194, v193, 0.15915494, -v194
	v_mul_f32_e32 v194, 0x40c90fdb, v194
	v_mul_f32_e32 v194, 0.15915494, v194
	v_sin_f32_e32 v209, v194
	v_cos_f32_e32 v201, v194
	v_mul_f32_e32 v193, 0x385f10c4, v182
	v_mul_f32_e32 v194, 0.15915494, v193
	v_rndne_f32_e32 v194, v194
	v_fma_f32 v194, v193, 0.15915494, -v194
	v_mul_f32_e32 v194, 0x40c90fdb, v194
	v_mul_f32_e32 v194, 0.15915494, v194
	v_sin_f32_e32 v210, v194
	v_cos_f32_e32 v202, v194
	v_mul_f32_e32 v193, 0x372d07a7, v182
	v_mul_f32_e32 v194, 0.15915494, v193
	v_rndne_f32_e32 v194, v194
	v_fma_f32 v194, v193, 0.15915494, -v194
	v_mul_f32_e32 v194, 0x40c90fdb, v194
	v_mul_f32_e32 v194, 0.15915494, v194
	v_sin_f32_e32 v211, v194
	v_cos_f32_e32 v203, v194
	s_waitcnt lgkmcnt(0)
	v_mul_f32_e32 v204, v204, v184
	v_mul_f32_e32 v196, v196, v24
	v_mul_f32_e32 v204, v204, v192
	v_add_f32_e32 v196, v196, v204
	v_cndmask_b32_e64 v32, v24, v196, s[68:69]
	v_mul_f32_e32 v205, v205, v185
	v_mul_f32_e32 v197, v197, v25
	v_mul_f32_e32 v205, v205, v192
	v_add_f32_e32 v197, v197, v205
	v_cndmask_b32_e64 v33, v25, v197, s[68:69]
	v_mul_f32_e32 v206, v206, v186
	v_mul_f32_e32 v198, v198, v26
	v_mul_f32_e32 v206, v206, v192
	v_add_f32_e32 v198, v198, v206
	v_cndmask_b32_e64 v34, v26, v198, s[68:69]
	v_mul_f32_e32 v207, v207, v187
	v_mul_f32_e32 v199, v199, v27
	v_mul_f32_e32 v207, v207, v192
	v_add_f32_e32 v199, v199, v207
	v_cndmask_b32_e64 v35, v27, v199, s[68:69]
	v_mul_f32_e32 v208, v208, v188
	v_mul_f32_e32 v200, v200, v28
	v_mul_f32_e32 v208, v208, v192
	v_add_f32_e32 v200, v200, v208
	v_cndmask_b32_e64 v36, v28, v200, s[68:69]
	v_mul_f32_e32 v209, v209, v189
	v_mul_f32_e32 v201, v201, v29
	v_mul_f32_e32 v209, v209, v192
	v_add_f32_e32 v201, v201, v209
	v_cndmask_b32_e64 v37, v29, v201, s[68:69]
	v_mul_f32_e32 v210, v210, v190
	v_mul_f32_e32 v202, v202, v30
	v_mul_f32_e32 v210, v210, v192
	v_add_f32_e32 v202, v202, v210
	v_cndmask_b32_e64 v38, v30, v202, s[68:69]
	v_mul_f32_e32 v211, v211, v191
	v_mul_f32_e32 v203, v203, v31
	v_mul_f32_e32 v211, v211, v192
	v_add_f32_e32 v203, v203, v211
	v_cndmask_b32_e64 v39, v31, v203, s[68:69]
	s_branch .LBB0_787

.LBB0_787:
	v_mov_b64_e32 v[28:29], s[78:79]
	v_mad_i64_i32 v[28:29], s[28:29], v40, s26, v[28:29]
	v_cvt_pk_bf16_f32 v24, v32, v33
	v_cvt_pk_bf16_f32 v25, v34, v35
	v_cvt_pk_bf16_f32 v26, v36, v37
	v_cvt_pk_bf16_f32 v27, v38, v39
	v_lshl_add_u64 v[28:29], v[64:65], 1, v[28:29]
	s_and_b64 vcc, exec, s[38:39]
	v_add_u32_e32 v32, 0x90, v181
	s_waitcnt lgkmcnt(0)
	s_add_u32 s68, s30, 0x63100
	s_addc_u32 s69, s31, 0
	global_store_dwordx4 v213, v[218:221], s[68:69] nt
	ds_bpermute_b32 v214, v212, v24
	ds_bpermute_b32 v215, v212, v25
	ds_bpermute_b32 v216, v212, v26
	ds_bpermute_b32 v217, v212, v27
	s_cbranch_vccnz .LBB0_837
	v_add_u32_e32 v182, 144, v181
	v_xor_b32_e32 v183, 16, v180
	v_and_b32_e32 v182, 0xfff, v182
	v_lshlrev_b32_e32 v183, 2, v183
	v_cvt_f32_u32_e32 v182, v182
	v_cmp_eq_u32_e64 s[60:61], 0, v171
	v_cmp_gt_u32_e64 s[68:69], 2, v171
	ds_bpermute_b32 v184, v183, v16
	ds_bpermute_b32 v185, v183, v17
	ds_bpermute_b32 v186, v183, v18
	ds_bpermute_b32 v187, v183, v19
	ds_bpermute_b32 v188, v183, v20
	ds_bpermute_b32 v189, v183, v21
	ds_bpermute_b32 v190, v183, v22
	ds_bpermute_b32 v191, v183, v23
	v_mov_b32_e32 v192, 1.0
	v_cndmask_b32_e64 v192, v192, -1.0, s[60:61]
	v_mul_f32_e32 v194, 0.15915494, v182
	v_rndne_f32_e32 v194, v194
	v_fma_f32 v194, v182, 0.15915494, -v194
	v_mul_f32_e32 v194, 0x40c90fdb, v194
	v_mul_f32_e32 v194, 0.15915494, v194
	v_sin_f32_e32 v204, v194
	v_cos_f32_e32 v196, v194
	v_mul_f32_e32 v193, 0x3e4693af, v182
	v_mul_f32_e32 v194, 0.15915494, v193
	v_rndne_f32_e32 v194, v194
	v_fma_f32 v194, v193, 0.15915494, -v194
	v_mul_f32_e32 v194, 0x40c90fdb, v194
	v_mul_f32_e32 v194, 0.15915494, v194
	v_sin_f32_e32 v205, v194
	v_cos_f32_e32 v197, v194
	v_mul_f32_e32 v193, 0x3d1a08c8, v182
	v_mul_f32_e32 v194, 0.15915494, v193
	v_rndne_f32_e32 v194, v194
	v_fma_f32 v194, v193, 0.15915494, -v194
	v_mul_f32_e32 v194, 0x40c90fdb, v194
	v_mul_f32_e32 v194, 0.15915494, v194
	v_sin_f32_e32 v206, v194
	v_cos_f32_e32 v198, v194
	v_mul_f32_e32 v193, 0x3beef74e, v182
	v_mul_f32_e32 v194, 0.15915494, v193
	v_rndne_f32_e32 v194, v194
	v_fma_f32 v194, v193, 0.15915494, -v194
	v_mul_f32_e32 v194, 0x40c90fdb, v194
	v_mul_f32_e32 v194, 0.15915494, v194
	v_sin_f32_e32 v207, v194
	v_cos_f32_e32 v199, v194
	v_mul_f32_e32 v193, 0x3ab95d22, v182
	v_mul_f32_e32 v194, 0.15915494, v193
	v_rndne_f32_e32 v194, v194
	v_fma_f32 v194, v193, 0.15915494, -v194
	v_mul_f32_e32 v194, 0x40c90fdb, v194
	v_mul_f32_e32 v194, 0.15915494, v194
	v_sin_f32_e32 v208, v194
	v_cos_f32_e32 v200, v194
	v_mul_f32_e32 v193, 0x398fc8f8, v182
	v_mul_f32_e32 v194, 0.15915494, v193
	v_rndne_f32_e32 v194, v194
	v_fma_f32 v194, v193, 0.15915494, -v194
	v_mul_f32_e32 v194, 0x40c90fdb, v194
	v_mul_f32_e32 v194, 0.15915494, v194
	v_sin_f32_e32 v209, v194
	v_cos_f32_e32 v201, v194
	v_mul_f32_e32 v193, 0x385f10c4, v182
	v_mul_f32_e32 v194, 0.15915494, v193
	v_rndne_f32_e32 v194, v194
	v_fma_f32 v194, v193, 0.15915494, -v194
	v_mul_f32_e32 v194, 0x40c90fdb, v194
	v_mul_f32_e32 v194, 0.15915494, v194
	v_sin_f32_e32 v210, v194
	v_cos_f32_e32 v202, v194
	v_mul_f32_e32 v193, 0x372d07a7, v182
	v_mul_f32_e32 v194, 0.15915494, v193
	v_rndne_f32_e32 v194, v194
	v_fma_f32 v194, v193, 0.15915494, -v194
	v_mul_f32_e32 v194, 0x40c90fdb, v194
	v_mul_f32_e32 v194, 0.15915494, v194
	v_sin_f32_e32 v211, v194
	v_cos_f32_e32 v203, v194
	s_waitcnt lgkmcnt(0)
	v_mul_f32_e32 v204, v204, v184
	v_mul_f32_e32 v196, v196, v16
	v_mul_f32_e32 v204, v204, v192
	v_add_f32_e32 v196, v196, v204
	v_cndmask_b32_e64 v24, v16, v196, s[68:69]
	v_mul_f32_e32 v205, v205, v185
	v_mul_f32_e32 v197, v197, v17
	v_mul_f32_e32 v205, v205, v192
	v_add_f32_e32 v197, v197, v205
	v_cndmask_b32_e64 v25, v17, v197, s[68:69]
	v_mul_f32_e32 v206, v206, v186
	v_mul_f32_e32 v198, v198, v18
	v_mul_f32_e32 v206, v206, v192
	v_add_f32_e32 v198, v198, v206
	v_cndmask_b32_e64 v26, v18, v198, s[68:69]
	v_mul_f32_e32 v207, v207, v187
	v_mul_f32_e32 v199, v199, v19
	v_mul_f32_e32 v207, v207, v192
	v_add_f32_e32 v199, v199, v207
	v_cndmask_b32_e64 v27, v19, v199, s[68:69]
	v_mul_f32_e32 v208, v208, v188
	v_mul_f32_e32 v200, v200, v20
	v_mul_f32_e32 v208, v208, v192
	v_add_f32_e32 v200, v200, v208
	v_cndmask_b32_e64 v28, v20, v200, s[68:69]
	v_mul_f32_e32 v209, v209, v189
	v_mul_f32_e32 v201, v201, v21
	v_mul_f32_e32 v209, v209, v192
	v_add_f32_e32 v201, v201, v209
	v_cndmask_b32_e64 v29, v21, v201, s[68:69]
	v_mul_f32_e32 v210, v210, v190
	v_mul_f32_e32 v202, v202, v22
	v_mul_f32_e32 v210, v210, v192
	v_add_f32_e32 v202, v202, v210
	v_cndmask_b32_e64 v30, v22, v202, s[68:69]
	v_mul_f32_e32 v211, v211, v191
	v_mul_f32_e32 v203, v203, v23
	v_mul_f32_e32 v211, v211, v192
	v_add_f32_e32 v203, v203, v211
	v_cndmask_b32_e64 v31, v23, v203, s[68:69]
	s_branch .LBB0_838

.LBB0_838:
	v_mov_b64_e32 v[20:21], s[78:79]
	v_mad_i64_i32 v[20:21], s[28:29], v32, s26, v[20:21]
	v_cvt_pk_bf16_f32 v16, v24, v25
	v_cvt_pk_bf16_f32 v17, v26, v27
	v_cvt_pk_bf16_f32 v18, v28, v29
	v_cvt_pk_bf16_f32 v19, v30, v31
	v_lshl_add_u64 v[20:21], v[64:65], 1, v[20:21]
	s_and_b64 vcc, exec, s[38:39]
	v_add_u32_e32 v24, 0xa0, v181
	s_waitcnt lgkmcnt(0)
	s_add_u32 s68, s30, 0x108100
	s_addc_u32 s69, s31, 0
	global_store_dwordx4 v213, v[214:217], s[68:69] nt
	ds_bpermute_b32 v218, v212, v16
	ds_bpermute_b32 v219, v212, v17
	ds_bpermute_b32 v220, v212, v18
	ds_bpermute_b32 v221, v212, v19
	s_cbranch_vccnz .LBB0_888
	v_add_u32_e32 v182, 160, v181
	v_xor_b32_e32 v183, 16, v180
	v_and_b32_e32 v182, 0xfff, v182
	v_lshlrev_b32_e32 v183, 2, v183
	v_cvt_f32_u32_e32 v182, v182
	v_cmp_eq_u32_e64 s[60:61], 0, v171
	v_cmp_gt_u32_e64 s[68:69], 2, v171
	ds_bpermute_b32 v184, v183, v8
	ds_bpermute_b32 v185, v183, v9
	ds_bpermute_b32 v186, v183, v10
	ds_bpermute_b32 v187, v183, v11
	ds_bpermute_b32 v188, v183, v12
	ds_bpermute_b32 v189, v183, v13
	ds_bpermute_b32 v190, v183, v14
	ds_bpermute_b32 v191, v183, v15
	v_mov_b32_e32 v192, 1.0
	v_cndmask_b32_e64 v192, v192, -1.0, s[60:61]
	v_mul_f32_e32 v194, 0.15915494, v182
	v_rndne_f32_e32 v194, v194
	v_fma_f32 v194, v182, 0.15915494, -v194
	v_mul_f32_e32 v194, 0x40c90fdb, v194
	v_mul_f32_e32 v194, 0.15915494, v194
	v_sin_f32_e32 v204, v194
	v_cos_f32_e32 v196, v194
	v_mul_f32_e32 v193, 0x3e4693af, v182
	v_mul_f32_e32 v194, 0.15915494, v193
	v_rndne_f32_e32 v194, v194
	v_fma_f32 v194, v193, 0.15915494, -v194
	v_mul_f32_e32 v194, 0x40c90fdb, v194
	v_mul_f32_e32 v194, 0.15915494, v194
	v_sin_f32_e32 v205, v194
	v_cos_f32_e32 v197, v194
	v_mul_f32_e32 v193, 0x3d1a08c8, v182
	v_mul_f32_e32 v194, 0.15915494, v193
	v_rndne_f32_e32 v194, v194
	v_fma_f32 v194, v193, 0.15915494, -v194
	v_mul_f32_e32 v194, 0x40c90fdb, v194
	v_mul_f32_e32 v194, 0.15915494, v194
	v_sin_f32_e32 v206, v194
	v_cos_f32_e32 v198, v194
	v_mul_f32_e32 v193, 0x3beef74e, v182
	v_mul_f32_e32 v194, 0.15915494, v193
	v_rndne_f32_e32 v194, v194
	v_fma_f32 v194, v193, 0.15915494, -v194
	v_mul_f32_e32 v194, 0x40c90fdb, v194
	v_mul_f32_e32 v194, 0.15915494, v194
	v_sin_f32_e32 v207, v194
	v_cos_f32_e32 v199, v194
	v_mul_f32_e32 v193, 0x3ab95d22, v182
	v_mul_f32_e32 v194, 0.15915494, v193
	v_rndne_f32_e32 v194, v194
	v_fma_f32 v194, v193, 0.15915494, -v194
	v_mul_f32_e32 v194, 0x40c90fdb, v194
	v_mul_f32_e32 v194, 0.15915494, v194
	v_sin_f32_e32 v208, v194
	v_cos_f32_e32 v200, v194
	v_mul_f32_e32 v193, 0x398fc8f8, v182
	v_mul_f32_e32 v194, 0.15915494, v193
	v_rndne_f32_e32 v194, v194
	v_fma_f32 v194, v193, 0.15915494, -v194
	v_mul_f32_e32 v194, 0x40c90fdb, v194
	v_mul_f32_e32 v194, 0.15915494, v194
	v_sin_f32_e32 v209, v194
	v_cos_f32_e32 v201, v194
	v_mul_f32_e32 v193, 0x385f10c4, v182
	v_mul_f32_e32 v194, 0.15915494, v193
	v_rndne_f32_e32 v194, v194
	v_fma_f32 v194, v193, 0.15915494, -v194
	v_mul_f32_e32 v194, 0x40c90fdb, v194
	v_mul_f32_e32 v194, 0.15915494, v194
	v_sin_f32_e32 v210, v194
	v_cos_f32_e32 v202, v194
	v_mul_f32_e32 v193, 0x372d07a7, v182
	v_mul_f32_e32 v194, 0.15915494, v193
	v_rndne_f32_e32 v194, v194
	v_fma_f32 v194, v193, 0.15915494, -v194
	v_mul_f32_e32 v194, 0x40c90fdb, v194
	v_mul_f32_e32 v194, 0.15915494, v194
	v_sin_f32_e32 v211, v194
	v_cos_f32_e32 v203, v194
	s_waitcnt lgkmcnt(0)
	v_mul_f32_e32 v204, v204, v184
	v_mul_f32_e32 v196, v196, v8
	v_mul_f32_e32 v204, v204, v192
	v_add_f32_e32 v196, v196, v204
	v_cndmask_b32_e64 v16, v8, v196, s[68:69]
	v_mul_f32_e32 v205, v205, v185
	v_mul_f32_e32 v197, v197, v9
	v_mul_f32_e32 v205, v205, v192
	v_add_f32_e32 v197, v197, v205
	v_cndmask_b32_e64 v17, v9, v197, s[68:69]
	v_mul_f32_e32 v206, v206, v186
	v_mul_f32_e32 v198, v198, v10
	v_mul_f32_e32 v206, v206, v192
	v_add_f32_e32 v198, v198, v206
	v_cndmask_b32_e64 v18, v10, v198, s[68:69]
	v_mul_f32_e32 v207, v207, v187
	v_mul_f32_e32 v199, v199, v11
	v_mul_f32_e32 v207, v207, v192
	v_add_f32_e32 v199, v199, v207
	v_cndmask_b32_e64 v19, v11, v199, s[68:69]
	v_mul_f32_e32 v208, v208, v188
	v_mul_f32_e32 v200, v200, v12
	v_mul_f32_e32 v208, v208, v192
	v_add_f32_e32 v200, v200, v208
	v_cndmask_b32_e64 v20, v12, v200, s[68:69]
	v_mul_f32_e32 v209, v209, v189
	v_mul_f32_e32 v201, v201, v13
	v_mul_f32_e32 v209, v209, v192
	v_add_f32_e32 v201, v201, v209
	v_cndmask_b32_e64 v21, v13, v201, s[68:69]
	v_mul_f32_e32 v210, v210, v190
	v_mul_f32_e32 v202, v202, v14
	v_mul_f32_e32 v210, v210, v192
	v_add_f32_e32 v202, v202, v210
	v_cndmask_b32_e64 v22, v14, v202, s[68:69]
	v_mul_f32_e32 v211, v211, v191
	v_mul_f32_e32 v203, v203, v15
	v_mul_f32_e32 v211, v211, v192
	v_add_f32_e32 v203, v203, v211
	v_cndmask_b32_e64 v23, v15, v203, s[68:69]
	s_branch .LBB0_889

.LBB0_889:
	v_mov_b64_e32 v[12:13], s[78:79]
	v_mad_i64_i32 v[12:13], s[28:29], v24, s26, v[12:13]
	v_cvt_pk_bf16_f32 v8, v16, v17
	v_cvt_pk_bf16_f32 v9, v18, v19
	v_cvt_pk_bf16_f32 v10, v20, v21
	v_cvt_pk_bf16_f32 v11, v22, v23
	v_lshl_add_u64 v[12:13], v[64:65], 1, v[12:13]
	s_and_b64 vcc, exec, s[38:39]
	v_add_u32_e32 v16, 0xb0, v181
	s_waitcnt lgkmcnt(0)
	s_add_u32 s68, s30, 0x129100
	s_addc_u32 s69, s31, 0
	global_store_dwordx4 v213, v[218:221], s[68:69] nt
	ds_bpermute_b32 v214, v212, v8
	ds_bpermute_b32 v215, v212, v9
	ds_bpermute_b32 v216, v212, v10
	ds_bpermute_b32 v217, v212, v11
	s_cbranch_vccnz .LBB0_939
	v_add_u32_e32 v182, 176, v181
	v_xor_b32_e32 v183, 16, v180
	v_and_b32_e32 v182, 0xfff, v182
	v_lshlrev_b32_e32 v183, 2, v183
	v_cvt_f32_u32_e32 v182, v182
	v_cmp_eq_u32_e64 s[60:61], 0, v171
	v_cmp_gt_u32_e64 s[68:69], 2, v171
	ds_bpermute_b32 v184, v183, v0
	ds_bpermute_b32 v185, v183, v1
	ds_bpermute_b32 v186, v183, v2
	ds_bpermute_b32 v187, v183, v3
	ds_bpermute_b32 v188, v183, v4
	ds_bpermute_b32 v189, v183, v5
	ds_bpermute_b32 v190, v183, v6
	ds_bpermute_b32 v191, v183, v7
	v_mov_b32_e32 v192, 1.0
	v_cndmask_b32_e64 v192, v192, -1.0, s[60:61]
	v_mul_f32_e32 v194, 0.15915494, v182
	v_rndne_f32_e32 v194, v194
	v_fma_f32 v194, v182, 0.15915494, -v194
	v_mul_f32_e32 v194, 0x40c90fdb, v194
	v_mul_f32_e32 v194, 0.15915494, v194
	v_sin_f32_e32 v204, v194
	v_cos_f32_e32 v196, v194
	v_mul_f32_e32 v193, 0x3e4693af, v182
	v_mul_f32_e32 v194, 0.15915494, v193
	v_rndne_f32_e32 v194, v194
	v_fma_f32 v194, v193, 0.15915494, -v194
	v_mul_f32_e32 v194, 0x40c90fdb, v194
	v_mul_f32_e32 v194, 0.15915494, v194
	v_sin_f32_e32 v205, v194
	v_cos_f32_e32 v197, v194
	v_mul_f32_e32 v193, 0x3d1a08c8, v182
	v_mul_f32_e32 v194, 0.15915494, v193
	v_rndne_f32_e32 v194, v194
	v_fma_f32 v194, v193, 0.15915494, -v194
	v_mul_f32_e32 v194, 0x40c90fdb, v194
	v_mul_f32_e32 v194, 0.15915494, v194
	v_sin_f32_e32 v206, v194
	v_cos_f32_e32 v198, v194
	v_mul_f32_e32 v193, 0x3beef74e, v182
	v_mul_f32_e32 v194, 0.15915494, v193
	v_rndne_f32_e32 v194, v194
	v_fma_f32 v194, v193, 0.15915494, -v194
	v_mul_f32_e32 v194, 0x40c90fdb, v194
	v_mul_f32_e32 v194, 0.15915494, v194
	v_sin_f32_e32 v207, v194
	v_cos_f32_e32 v199, v194
	v_mul_f32_e32 v193, 0x3ab95d22, v182
	v_mul_f32_e32 v194, 0.15915494, v193
	v_rndne_f32_e32 v194, v194
	v_fma_f32 v194, v193, 0.15915494, -v194
	v_mul_f32_e32 v194, 0x40c90fdb, v194
	v_mul_f32_e32 v194, 0.15915494, v194
	v_sin_f32_e32 v208, v194
	v_cos_f32_e32 v200, v194
	v_mul_f32_e32 v193, 0x398fc8f8, v182
	v_mul_f32_e32 v194, 0.15915494, v193
	v_rndne_f32_e32 v194, v194
	v_fma_f32 v194, v193, 0.15915494, -v194
	v_mul_f32_e32 v194, 0x40c90fdb, v194
	v_mul_f32_e32 v194, 0.15915494, v194
	v_sin_f32_e32 v209, v194
	v_cos_f32_e32 v201, v194
	v_mul_f32_e32 v193, 0x385f10c4, v182
	v_mul_f32_e32 v194, 0.15915494, v193
	v_rndne_f32_e32 v194, v194
	v_fma_f32 v194, v193, 0.15915494, -v194
	v_mul_f32_e32 v194, 0x40c90fdb, v194
	v_mul_f32_e32 v194, 0.15915494, v194
	v_sin_f32_e32 v210, v194
	v_cos_f32_e32 v202, v194
	v_mul_f32_e32 v193, 0x372d07a7, v182
	v_mul_f32_e32 v194, 0.15915494, v193
	v_rndne_f32_e32 v194, v194
	v_fma_f32 v194, v193, 0.15915494, -v194
	v_mul_f32_e32 v194, 0x40c90fdb, v194
	v_mul_f32_e32 v194, 0.15915494, v194
	v_sin_f32_e32 v211, v194
	v_cos_f32_e32 v203, v194
	s_waitcnt lgkmcnt(0)
	v_mul_f32_e32 v204, v204, v184
	v_mul_f32_e32 v196, v196, v0
	v_mul_f32_e32 v204, v204, v192
	v_add_f32_e32 v196, v196, v204
	v_cndmask_b32_e64 v8, v0, v196, s[68:69]
	v_mul_f32_e32 v205, v205, v185
	v_mul_f32_e32 v197, v197, v1
	v_mul_f32_e32 v205, v205, v192
	v_add_f32_e32 v197, v197, v205
	v_cndmask_b32_e64 v9, v1, v197, s[68:69]
	v_mul_f32_e32 v206, v206, v186
	v_mul_f32_e32 v198, v198, v2
	v_mul_f32_e32 v206, v206, v192
	v_add_f32_e32 v198, v198, v206
	v_cndmask_b32_e64 v10, v2, v198, s[68:69]
	v_mul_f32_e32 v207, v207, v187
	v_mul_f32_e32 v199, v199, v3
	v_mul_f32_e32 v207, v207, v192
	v_add_f32_e32 v199, v199, v207
	v_cndmask_b32_e64 v11, v3, v199, s[68:69]
	v_mul_f32_e32 v208, v208, v188
	v_mul_f32_e32 v200, v200, v4
	v_mul_f32_e32 v208, v208, v192
	v_add_f32_e32 v200, v200, v208
	v_cndmask_b32_e64 v12, v4, v200, s[68:69]
	v_mul_f32_e32 v209, v209, v189
	v_mul_f32_e32 v201, v201, v5
	v_mul_f32_e32 v209, v209, v192
	v_add_f32_e32 v201, v201, v209
	v_cndmask_b32_e64 v13, v5, v201, s[68:69]
	v_mul_f32_e32 v210, v210, v190
	v_mul_f32_e32 v202, v202, v6
	v_mul_f32_e32 v210, v210, v192
	v_add_f32_e32 v202, v202, v210
	v_cndmask_b32_e64 v14, v6, v202, s[68:69]
	v_mul_f32_e32 v211, v211, v191
	v_mul_f32_e32 v203, v203, v7
	v_mul_f32_e32 v211, v211, v192
	v_add_f32_e32 v203, v203, v211
	v_cndmask_b32_e64 v15, v7, v203, s[68:69]
	s_branch .LBB0_940

.LBB0_940:
	v_mov_b64_e32 v[4:5], s[78:79]
	v_mad_i64_i32 v[4:5], s[28:29], v16, s26, v[4:5]
	v_cvt_pk_bf16_f32 v0, v8, v9
	v_cvt_pk_bf16_f32 v1, v10, v11
	v_cvt_pk_bf16_f32 v2, v12, v13
	v_cvt_pk_bf16_f32 v3, v14, v15
	v_lshl_add_u64 v[4:5], v[64:65], 1, v[4:5]
	s_waitcnt lgkmcnt(0)
	s_add_u32 s68, s30, 0x14a100
	s_addc_u32 s69, s31, 0
	global_store_dwordx4 v213, v[214:217], s[68:69] nt
	ds_bpermute_b32 v218, v212, v0
	ds_bpermute_b32 v219, v212, v1
	ds_bpermute_b32 v220, v212, v2
	ds_bpermute_b32 v221, v212, v3
	s_waitcnt lgkmcnt(0)
	s_add_u32 s68, s30, 0x16b100
	s_addc_u32 s69, s31, 0
	global_store_dwordx4 v213, v[218:221], s[68:69] nt
	s_andn2_b64 vcc, exec, s[36:37]
	s_mov_b64 s[36:37], -1
	s_cbranch_vccnz .LBB0_113
